# LoRA matmuls of rw_lora and the post1 gate LoRA moved from VALU FMA loops to f32-operand MFMA (v_mfma_f32_16x16x4_f32); hand-written HGRN2 staging branch
# speedup vs baseline: 1.0800x; 1.0275x over previous
.LBB0_968:
	s_or_b64 exec, exec, s[0:1]
	s_waitcnt vmcnt(0)
	v_lshlrev_b32_e32 v24, 16, v17
	v_pk_add_f32 v[20:21], v[20:21], v[24:25] op_sel_hi:[1,0] neg_lo:[0,1] neg_hi:[0,1]
	s_mov_b64 s[0:1], 0
	v_pk_mul_f32 v[20:21], v[22:23], v[20:21]
	s_mov_b32 s10, 0
	v_add_f32_e32 v17, v20, v24
	v_mov_b32_e32 v20, 0
	v_add_f32_e32 v17, v17, v21
	v_mov_b32_e32 v21, v20
	v_mov_b32_e32 v62, v20
	v_mov_b32_e32 v63, v20
	v_mov_b32_e32 v56, v20
	v_mov_b32_e32 v57, v20
	v_mov_b32_e32 v50, v20
	v_mov_b32_e32 v51, v20
	v_mov_b32_e32 v44, v20
	v_mov_b32_e32 v45, v20
	v_mov_b32_e32 v38, v20
	v_mov_b32_e32 v39, v20
	v_mov_b32_e32 v32, v20
	v_mov_b32_e32 v33, v20
	v_mov_b32_e32 v26, v20
	v_mov_b32_e32 v27, v20
	v_mov_b32_e32 v22, v20
	v_mov_b32_e32 v23, v20
	v_mov_b32_e32 v64, v20
	v_mov_b32_e32 v65, v20
	v_mov_b32_e32 v58, v20
	v_mov_b32_e32 v59, v20
	v_mov_b32_e32 v52, v20
	v_mov_b32_e32 v53, v20
	v_mov_b32_e32 v46, v20
	v_mov_b32_e32 v47, v20
	v_mov_b32_e32 v40, v20
	v_mov_b32_e32 v41, v20
	v_mov_b32_e32 v34, v20
	v_mov_b32_e32 v35, v20
	v_mov_b32_e32 v28, v20
	v_mov_b32_e32 v29, v20
	v_mov_b32_e32 v24, v20
	v_mov_b32_e32 v25, v20
	v_mov_b32_e32 v30, v20
	v_mov_b32_e32 v31, v20
	v_mov_b32_e32 v36, v20
	v_mov_b32_e32 v37, v20
	v_mov_b32_e32 v42, v20
	v_mov_b32_e32 v43, v20
	v_mov_b32_e32 v48, v20
	v_mov_b32_e32 v49, v20
	v_mov_b32_e32 v54, v20
	v_mov_b32_e32 v55, v20
	v_mov_b32_e32 v60, v20
	v_mov_b32_e32 v61, v20
	v_mov_b32_e32 v66, v20
	v_mov_b32_e32 v67, v20
	ds_write_b32 v70, v17 offset:4096
	s_waitcnt lgkmcnt(0)
	s_barrier
	v_and_b32_e32 v112, 63, v164
	v_lshrrev_b32_e32 v113, 6, v164
	v_lshlrev_b32_e32 v107, 2, v112
	v_lshrrev_b32_e32 v114, 4, v112
	v_and_b32_e32 v115, 15, v112
	v_lshlrev_b32_e32 v111, 11, v114
	v_lshl_add_u32 v111, v113, 8, v111
	v_lshl_add_u32 v111, v115, 4, v111
	v_mul_u32_u24_e32 v110, 0x3000, v113
	v_add_u32_e32 v110, 0x2000, v110
	v_lshl_add_u32 v109, v114, 10, v110
	v_lshl_add_u32 v109, v115, 4, v109
	v_lshl_add_u32 v110, v112, 2, v110
	v_readlane_b32 s0, v255, 27
	v_readlane_b32 s1, v255, 28
	v_mov_b32_e32 v108, v111
	v_mov_b32_e32 v76, 0
	v_mov_b32_e32 v77, 0
	v_mov_b32_e32 v78, 0
	v_mov_b32_e32 v79, 0
	v_mov_b32_e32 v80, 0
	v_mov_b32_e32 v81, 0
	v_mov_b32_e32 v82, 0
	v_mov_b32_e32 v83, 0
	v_mov_b32_e32 v84, 0
	v_mov_b32_e32 v85, 0
	v_mov_b32_e32 v86, 0
	v_mov_b32_e32 v87, 0
	v_mov_b32_e32 v88, 0
	v_mov_b32_e32 v89, 0
	v_mov_b32_e32 v90, 0
	v_mov_b32_e32 v91, 0
	global_load_dwordx4 v[92:95], v108, s[0:1]
	v_add_u32_e32 v108, 0x2000, v108
	ds_read_b32 v104, v107 offset:0
	global_load_dwordx4 v[96:99], v108, s[0:1]
	v_add_u32_e32 v108, 0x2000, v108
	ds_read_b32 v105, v107 offset:256
	global_load_dwordx4 v[100:103], v108, s[0:1]
	v_add_u32_e32 v108, 0x2000, v108
	ds_read_b32 v106, v107 offset:512
	s_waitcnt vmcnt(2) lgkmcnt(2)
	v_mfma_f32_16x16x4_f32 v[76:79], v104, v92, v[76:79]
	v_mfma_f32_16x16x4_f32 v[80:83], v104, v93, v[80:83]
	v_mfma_f32_16x16x4_f32 v[84:87], v104, v94, v[84:87]
	v_mfma_f32_16x16x4_f32 v[88:91], v104, v95, v[88:91]
	global_load_dwordx4 v[92:95], v108, s[0:1]
	v_add_u32_e32 v108, 0x2000, v108
	ds_read_b32 v104, v107 offset:768
	s_waitcnt vmcnt(2) lgkmcnt(2)
	v_mfma_f32_16x16x4_f32 v[76:79], v105, v96, v[76:79]
	v_mfma_f32_16x16x4_f32 v[80:83], v105, v97, v[80:83]
	v_mfma_f32_16x16x4_f32 v[84:87], v105, v98, v[84:87]
	v_mfma_f32_16x16x4_f32 v[88:91], v105, v99, v[88:91]
	global_load_dwordx4 v[96:99], v108, s[0:1]
	v_add_u32_e32 v108, 0x2000, v108
	ds_read_b32 v105, v107 offset:1024
	s_waitcnt vmcnt(2) lgkmcnt(2)
	v_mfma_f32_16x16x4_f32 v[76:79], v106, v100, v[76:79]
	v_mfma_f32_16x16x4_f32 v[80:83], v106, v101, v[80:83]
	v_mfma_f32_16x16x4_f32 v[84:87], v106, v102, v[84:87]
	v_mfma_f32_16x16x4_f32 v[88:91], v106, v103, v[88:91]
	global_load_dwordx4 v[100:103], v108, s[0:1]
	v_add_u32_e32 v108, 0x2000, v108
	ds_read_b32 v106, v107 offset:1280
	s_waitcnt vmcnt(2) lgkmcnt(2)
	v_mfma_f32_16x16x4_f32 v[76:79], v104, v92, v[76:79]
	v_mfma_f32_16x16x4_f32 v[80:83], v104, v93, v[80:83]
	v_mfma_f32_16x16x4_f32 v[84:87], v104, v94, v[84:87]
	v_mfma_f32_16x16x4_f32 v[88:91], v104, v95, v[88:91]
	global_load_dwordx4 v[92:95], v108, s[0:1]
	v_add_u32_e32 v108, 0x2000, v108
	ds_read_b32 v104, v107 offset:1536
	s_waitcnt vmcnt(2) lgkmcnt(2)
	v_mfma_f32_16x16x4_f32 v[76:79], v105, v96, v[76:79]
	v_mfma_f32_16x16x4_f32 v[80:83], v105, v97, v[80:83]
	v_mfma_f32_16x16x4_f32 v[84:87], v105, v98, v[84:87]
	v_mfma_f32_16x16x4_f32 v[88:91], v105, v99, v[88:91]
	global_load_dwordx4 v[96:99], v108, s[0:1]
	v_add_u32_e32 v108, 0x2000, v108
	ds_read_b32 v105, v107 offset:1792
	s_waitcnt vmcnt(2) lgkmcnt(2)
	v_mfma_f32_16x16x4_f32 v[76:79], v106, v100, v[76:79]
	v_mfma_f32_16x16x4_f32 v[80:83], v106, v101, v[80:83]
	v_mfma_f32_16x16x4_f32 v[84:87], v106, v102, v[84:87]
	v_mfma_f32_16x16x4_f32 v[88:91], v106, v103, v[88:91]
	global_load_dwordx4 v[100:103], v108, s[0:1]
	v_add_u32_e32 v108, 0x2000, v108
	ds_read_b32 v106, v107 offset:2048
	s_waitcnt vmcnt(2) lgkmcnt(2)
	v_mfma_f32_16x16x4_f32 v[76:79], v104, v92, v[76:79]
	v_mfma_f32_16x16x4_f32 v[80:83], v104, v93, v[80:83]
	v_mfma_f32_16x16x4_f32 v[84:87], v104, v94, v[84:87]
	v_mfma_f32_16x16x4_f32 v[88:91], v104, v95, v[88:91]
	global_load_dwordx4 v[92:95], v108, s[0:1]
	v_add_u32_e32 v108, 0x2000, v108
	ds_read_b32 v104, v107 offset:2304
	s_waitcnt vmcnt(2) lgkmcnt(2)
	v_mfma_f32_16x16x4_f32 v[76:79], v105, v96, v[76:79]
	v_mfma_f32_16x16x4_f32 v[80:83], v105, v97, v[80:83]
	v_mfma_f32_16x16x4_f32 v[84:87], v105, v98, v[84:87]
	v_mfma_f32_16x16x4_f32 v[88:91], v105, v99, v[88:91]
	global_load_dwordx4 v[96:99], v108, s[0:1]
	v_add_u32_e32 v108, 0x2000, v108
	ds_read_b32 v105, v107 offset:2560
	s_waitcnt vmcnt(2) lgkmcnt(2)
	v_mfma_f32_16x16x4_f32 v[76:79], v106, v100, v[76:79]
	v_mfma_f32_16x16x4_f32 v[80:83], v106, v101, v[80:83]
	v_mfma_f32_16x16x4_f32 v[84:87], v106, v102, v[84:87]
	v_mfma_f32_16x16x4_f32 v[88:91], v106, v103, v[88:91]
	global_load_dwordx4 v[100:103], v108, s[0:1]
	v_add_u32_e32 v108, 0x2000, v108
	ds_read_b32 v106, v107 offset:2816
	s_waitcnt vmcnt(2) lgkmcnt(2)
	v_mfma_f32_16x16x4_f32 v[76:79], v104, v92, v[76:79]
	v_mfma_f32_16x16x4_f32 v[80:83], v104, v93, v[80:83]
	v_mfma_f32_16x16x4_f32 v[84:87], v104, v94, v[84:87]
	v_mfma_f32_16x16x4_f32 v[88:91], v104, v95, v[88:91]
	global_load_dwordx4 v[92:95], v108, s[0:1]
	v_add_u32_e32 v108, 0x2000, v108
	ds_read_b32 v104, v107 offset:3072
	s_waitcnt vmcnt(2) lgkmcnt(2)
	v_mfma_f32_16x16x4_f32 v[76:79], v105, v96, v[76:79]
	v_mfma_f32_16x16x4_f32 v[80:83], v105, v97, v[80:83]
	v_mfma_f32_16x16x4_f32 v[84:87], v105, v98, v[84:87]
	v_mfma_f32_16x16x4_f32 v[88:91], v105, v99, v[88:91]
	global_load_dwordx4 v[96:99], v108, s[0:1]
	v_add_u32_e32 v108, 0x2000, v108
	ds_read_b32 v105, v107 offset:3328
	s_waitcnt vmcnt(2) lgkmcnt(2)
	v_mfma_f32_16x16x4_f32 v[76:79], v106, v100, v[76:79]
	v_mfma_f32_16x16x4_f32 v[80:83], v106, v101, v[80:83]
	v_mfma_f32_16x16x4_f32 v[84:87], v106, v102, v[84:87]
	v_mfma_f32_16x16x4_f32 v[88:91], v106, v103, v[88:91]
	global_load_dwordx4 v[100:103], v108, s[0:1]
	v_add_u32_e32 v108, 0x2000, v108
	ds_read_b32 v106, v107 offset:3584
	s_waitcnt vmcnt(2) lgkmcnt(2)
	v_mfma_f32_16x16x4_f32 v[76:79], v104, v92, v[76:79]
	v_mfma_f32_16x16x4_f32 v[80:83], v104, v93, v[80:83]
	v_mfma_f32_16x16x4_f32 v[84:87], v104, v94, v[84:87]
	v_mfma_f32_16x16x4_f32 v[88:91], v104, v95, v[88:91]
	global_load_dwordx4 v[92:95], v108, s[0:1]
	v_add_u32_e32 v108, 0x2000, v108
	ds_read_b32 v104, v107 offset:3840
	s_waitcnt vmcnt(2) lgkmcnt(2)
	v_mfma_f32_16x16x4_f32 v[76:79], v105, v96, v[76:79]
	v_mfma_f32_16x16x4_f32 v[80:83], v105, v97, v[80:83]
	v_mfma_f32_16x16x4_f32 v[84:87], v105, v98, v[84:87]
	v_mfma_f32_16x16x4_f32 v[88:91], v105, v99, v[88:91]
	s_waitcnt vmcnt(1) lgkmcnt(1)
	v_mfma_f32_16x16x4_f32 v[76:79], v106, v100, v[76:79]
	v_mfma_f32_16x16x4_f32 v[80:83], v106, v101, v[80:83]
	v_mfma_f32_16x16x4_f32 v[84:87], v106, v102, v[84:87]
	v_mfma_f32_16x16x4_f32 v[88:91], v106, v103, v[88:91]
	s_waitcnt vmcnt(0) lgkmcnt(0)
	v_mfma_f32_16x16x4_f32 v[76:79], v104, v92, v[76:79]
	v_mfma_f32_16x16x4_f32 v[80:83], v104, v93, v[80:83]
	v_mfma_f32_16x16x4_f32 v[84:87], v104, v94, v[84:87]
	v_mfma_f32_16x16x4_f32 v[88:91], v104, v95, v[88:91]
	s_nop 15
	s_nop 3
	ds_write_b32 v109, v76 offset:0
	ds_write_b32 v109, v77 offset:256
	ds_write_b32 v109, v78 offset:512
	ds_write_b32 v109, v79 offset:768
	ds_write_b32 v109, v80 offset:4
	ds_write_b32 v109, v81 offset:260
	ds_write_b32 v109, v82 offset:516
	ds_write_b32 v109, v83 offset:772
	ds_write_b32 v109, v84 offset:8
	ds_write_b32 v109, v85 offset:264
	ds_write_b32 v109, v86 offset:520
	ds_write_b32 v109, v87 offset:776
	ds_write_b32 v109, v88 offset:12
	ds_write_b32 v109, v89 offset:268
	ds_write_b32 v109, v90 offset:524
	ds_write_b32 v109, v91 offset:780
	s_waitcnt lgkmcnt(0)
	s_add_u32 s0, s0, 0x20000
	s_addc_u32 s1, s1, 0
	v_mov_b32_e32 v108, v111
	v_mov_b32_e32 v76, 0
	v_mov_b32_e32 v77, 0
	v_mov_b32_e32 v78, 0
	v_mov_b32_e32 v79, 0
	v_mov_b32_e32 v80, 0
	v_mov_b32_e32 v81, 0
	v_mov_b32_e32 v82, 0
	v_mov_b32_e32 v83, 0
	v_mov_b32_e32 v84, 0
	v_mov_b32_e32 v85, 0
	v_mov_b32_e32 v86, 0
	v_mov_b32_e32 v87, 0
	v_mov_b32_e32 v88, 0
	v_mov_b32_e32 v89, 0
	v_mov_b32_e32 v90, 0
	v_mov_b32_e32 v91, 0
	global_load_dwordx4 v[92:95], v108, s[0:1]
	v_add_u32_e32 v108, 0x2000, v108
	ds_read_b32 v104, v107 offset:0
	global_load_dwordx4 v[96:99], v108, s[0:1]
	v_add_u32_e32 v108, 0x2000, v108
	ds_read_b32 v105, v107 offset:256
	global_load_dwordx4 v[100:103], v108, s[0:1]
	v_add_u32_e32 v108, 0x2000, v108
	ds_read_b32 v106, v107 offset:512
	s_waitcnt vmcnt(2) lgkmcnt(2)
	v_mfma_f32_16x16x4_f32 v[76:79], v104, v92, v[76:79]
	v_mfma_f32_16x16x4_f32 v[80:83], v104, v93, v[80:83]
	v_mfma_f32_16x16x4_f32 v[84:87], v104, v94, v[84:87]
	v_mfma_f32_16x16x4_f32 v[88:91], v104, v95, v[88:91]
	global_load_dwordx4 v[92:95], v108, s[0:1]
	v_add_u32_e32 v108, 0x2000, v108
	ds_read_b32 v104, v107 offset:768
	s_waitcnt vmcnt(2) lgkmcnt(2)
	v_mfma_f32_16x16x4_f32 v[76:79], v105, v96, v[76:79]
	v_mfma_f32_16x16x4_f32 v[80:83], v105, v97, v[80:83]
	v_mfma_f32_16x16x4_f32 v[84:87], v105, v98, v[84:87]
	v_mfma_f32_16x16x4_f32 v[88:91], v105, v99, v[88:91]
	global_load_dwordx4 v[96:99], v108, s[0:1]
	v_add_u32_e32 v108, 0x2000, v108
	ds_read_b32 v105, v107 offset:1024
	s_waitcnt vmcnt(2) lgkmcnt(2)
	v_mfma_f32_16x16x4_f32 v[76:79], v106, v100, v[76:79]
	v_mfma_f32_16x16x4_f32 v[80:83], v106, v101, v[80:83]
	v_mfma_f32_16x16x4_f32 v[84:87], v106, v102, v[84:87]
	v_mfma_f32_16x16x4_f32 v[88:91], v106, v103, v[88:91]
	global_load_dwordx4 v[100:103], v108, s[0:1]
	v_add_u32_e32 v108, 0x2000, v108
	ds_read_b32 v106, v107 offset:1280
	s_waitcnt vmcnt(2) lgkmcnt(2)
	v_mfma_f32_16x16x4_f32 v[76:79], v104, v92, v[76:79]
	v_mfma_f32_16x16x4_f32 v[80:83], v104, v93, v[80:83]
	v_mfma_f32_16x16x4_f32 v[84:87], v104, v94, v[84:87]
	v_mfma_f32_16x16x4_f32 v[88:91], v104, v95, v[88:91]
	global_load_dwordx4 v[92:95], v108, s[0:1]
	v_add_u32_e32 v108, 0x2000, v108
	ds_read_b32 v104, v107 offset:1536
	s_waitcnt vmcnt(2) lgkmcnt(2)
	v_mfma_f32_16x16x4_f32 v[76:79], v105, v96, v[76:79]
	v_mfma_f32_16x16x4_f32 v[80:83], v105, v97, v[80:83]
	v_mfma_f32_16x16x4_f32 v[84:87], v105, v98, v[84:87]
	v_mfma_f32_16x16x4_f32 v[88:91], v105, v99, v[88:91]
	global_load_dwordx4 v[96:99], v108, s[0:1]
	v_add_u32_e32 v108, 0x2000, v108
	ds_read_b32 v105, v107 offset:1792
	s_waitcnt vmcnt(2) lgkmcnt(2)
	v_mfma_f32_16x16x4_f32 v[76:79], v106, v100, v[76:79]
	v_mfma_f32_16x16x4_f32 v[80:83], v106, v101, v[80:83]
	v_mfma_f32_16x16x4_f32 v[84:87], v106, v102, v[84:87]
	v_mfma_f32_16x16x4_f32 v[88:91], v106, v103, v[88:91]
	global_load_dwordx4 v[100:103], v108, s[0:1]
	v_add_u32_e32 v108, 0x2000, v108
	ds_read_b32 v106, v107 offset:2048
	s_waitcnt vmcnt(2) lgkmcnt(2)
	v_mfma_f32_16x16x4_f32 v[76:79], v104, v92, v[76:79]
	v_mfma_f32_16x16x4_f32 v[80:83], v104, v93, v[80:83]
	v_mfma_f32_16x16x4_f32 v[84:87], v104, v94, v[84:87]
	v_mfma_f32_16x16x4_f32 v[88:91], v104, v95, v[88:91]
	global_load_dwordx4 v[92:95], v108, s[0:1]
	v_add_u32_e32 v108, 0x2000, v108
	ds_read_b32 v104, v107 offset:2304
	s_waitcnt vmcnt(2) lgkmcnt(2)
	v_mfma_f32_16x16x4_f32 v[76:79], v105, v96, v[76:79]
	v_mfma_f32_16x16x4_f32 v[80:83], v105, v97, v[80:83]
	v_mfma_f32_16x16x4_f32 v[84:87], v105, v98, v[84:87]
	v_mfma_f32_16x16x4_f32 v[88:91], v105, v99, v[88:91]
	global_load_dwordx4 v[96:99], v108, s[0:1]
	v_add_u32_e32 v108, 0x2000, v108
	ds_read_b32 v105, v107 offset:2560
	s_waitcnt vmcnt(2) lgkmcnt(2)
	v_mfma_f32_16x16x4_f32 v[76:79], v106, v100, v[76:79]
	v_mfma_f32_16x16x4_f32 v[80:83], v106, v101, v[80:83]
	v_mfma_f32_16x16x4_f32 v[84:87], v106, v102, v[84:87]
	v_mfma_f32_16x16x4_f32 v[88:91], v106, v103, v[88:91]
	global_load_dwordx4 v[100:103], v108, s[0:1]
	v_add_u32_e32 v108, 0x2000, v108
	ds_read_b32 v106, v107 offset:2816
	s_waitcnt vmcnt(2) lgkmcnt(2)
	v_mfma_f32_16x16x4_f32 v[76:79], v104, v92, v[76:79]
	v_mfma_f32_16x16x4_f32 v[80:83], v104, v93, v[80:83]
	v_mfma_f32_16x16x4_f32 v[84:87], v104, v94, v[84:87]
	v_mfma_f32_16x16x4_f32 v[88:91], v104, v95, v[88:91]
	global_load_dwordx4 v[92:95], v108, s[0:1]
	v_add_u32_e32 v108, 0x2000, v108
	ds_read_b32 v104, v107 offset:3072
	s_waitcnt vmcnt(2) lgkmcnt(2)
	v_mfma_f32_16x16x4_f32 v[76:79], v105, v96, v[76:79]
	v_mfma_f32_16x16x4_f32 v[80:83], v105, v97, v[80:83]
	v_mfma_f32_16x16x4_f32 v[84:87], v105, v98, v[84:87]
	v_mfma_f32_16x16x4_f32 v[88:91], v105, v99, v[88:91]
	global_load_dwordx4 v[96:99], v108, s[0:1]
	v_add_u32_e32 v108, 0x2000, v108
	ds_read_b32 v105, v107 offset:3328
	s_waitcnt vmcnt(2) lgkmcnt(2)
	v_mfma_f32_16x16x4_f32 v[76:79], v106, v100, v[76:79]
	v_mfma_f32_16x16x4_f32 v[80:83], v106, v101, v[80:83]
	v_mfma_f32_16x16x4_f32 v[84:87], v106, v102, v[84:87]
	v_mfma_f32_16x16x4_f32 v[88:91], v106, v103, v[88:91]
	global_load_dwordx4 v[100:103], v108, s[0:1]
	v_add_u32_e32 v108, 0x2000, v108
	ds_read_b32 v106, v107 offset:3584
	s_waitcnt vmcnt(2) lgkmcnt(2)
	v_mfma_f32_16x16x4_f32 v[76:79], v104, v92, v[76:79]
	v_mfma_f32_16x16x4_f32 v[80:83], v104, v93, v[80:83]
	v_mfma_f32_16x16x4_f32 v[84:87], v104, v94, v[84:87]
	v_mfma_f32_16x16x4_f32 v[88:91], v104, v95, v[88:91]
	global_load_dwordx4 v[92:95], v108, s[0:1]
	v_add_u32_e32 v108, 0x2000, v108
	ds_read_b32 v104, v107 offset:3840
	s_waitcnt vmcnt(2) lgkmcnt(2)
	v_mfma_f32_16x16x4_f32 v[76:79], v105, v96, v[76:79]
	v_mfma_f32_16x16x4_f32 v[80:83], v105, v97, v[80:83]
	v_mfma_f32_16x16x4_f32 v[84:87], v105, v98, v[84:87]
	v_mfma_f32_16x16x4_f32 v[88:91], v105, v99, v[88:91]
	s_waitcnt vmcnt(1) lgkmcnt(1)
	v_mfma_f32_16x16x4_f32 v[76:79], v106, v100, v[76:79]
	v_mfma_f32_16x16x4_f32 v[80:83], v106, v101, v[80:83]
	v_mfma_f32_16x16x4_f32 v[84:87], v106, v102, v[84:87]
	v_mfma_f32_16x16x4_f32 v[88:91], v106, v103, v[88:91]
	s_waitcnt vmcnt(0) lgkmcnt(0)
	v_mfma_f32_16x16x4_f32 v[76:79], v104, v92, v[76:79]
	v_mfma_f32_16x16x4_f32 v[80:83], v104, v93, v[80:83]
	v_mfma_f32_16x16x4_f32 v[84:87], v104, v94, v[84:87]
	v_mfma_f32_16x16x4_f32 v[88:91], v104, v95, v[88:91]
	s_nop 15
	s_nop 3
	ds_write_b32 v109, v76 offset:4096
	ds_write_b32 v109, v77 offset:4352
	ds_write_b32 v109, v78 offset:4608
	ds_write_b32 v109, v79 offset:4864
	ds_write_b32 v109, v80 offset:4100
	ds_write_b32 v109, v81 offset:4356
	ds_write_b32 v109, v82 offset:4612
	ds_write_b32 v109, v83 offset:4868
	ds_write_b32 v109, v84 offset:4104
	ds_write_b32 v109, v85 offset:4360
	ds_write_b32 v109, v86 offset:4616
	ds_write_b32 v109, v87 offset:4872
	ds_write_b32 v109, v88 offset:4108
	ds_write_b32 v109, v89 offset:4364
	ds_write_b32 v109, v90 offset:4620
	ds_write_b32 v109, v91 offset:4876
	s_waitcnt lgkmcnt(0)
	v_readlane_b32 s0, v255, 31
	v_readlane_b32 s1, v255, 32
	v_mov_b32_e32 v108, v111
	v_mov_b32_e32 v76, 0
	v_mov_b32_e32 v77, 0
	v_mov_b32_e32 v78, 0
	v_mov_b32_e32 v79, 0
	v_mov_b32_e32 v80, 0
	v_mov_b32_e32 v81, 0
	v_mov_b32_e32 v82, 0
	v_mov_b32_e32 v83, 0
	v_mov_b32_e32 v84, 0
	v_mov_b32_e32 v85, 0
	v_mov_b32_e32 v86, 0
	v_mov_b32_e32 v87, 0
	v_mov_b32_e32 v88, 0
	v_mov_b32_e32 v89, 0
	v_mov_b32_e32 v90, 0
	v_mov_b32_e32 v91, 0
	global_load_dwordx4 v[92:95], v108, s[0:1]
	v_add_u32_e32 v108, 0x2000, v108
	ds_read_b32 v104, v107 offset:4096
	global_load_dwordx4 v[96:99], v108, s[0:1]
	v_add_u32_e32 v108, 0x2000, v108
	ds_read_b32 v105, v107 offset:4352
	global_load_dwordx4 v[100:103], v108, s[0:1]
	v_add_u32_e32 v108, 0x2000, v108
	ds_read_b32 v106, v107 offset:4608
	s_waitcnt vmcnt(2) lgkmcnt(2)
	v_mfma_f32_16x16x4_f32 v[76:79], v104, v92, v[76:79]
	v_mfma_f32_16x16x4_f32 v[80:83], v104, v93, v[80:83]
	v_mfma_f32_16x16x4_f32 v[84:87], v104, v94, v[84:87]
	v_mfma_f32_16x16x4_f32 v[88:91], v104, v95, v[88:91]
	global_load_dwordx4 v[92:95], v108, s[0:1]
	v_add_u32_e32 v108, 0x2000, v108
	ds_read_b32 v104, v107 offset:4864
	s_waitcnt vmcnt(2) lgkmcnt(2)
	v_mfma_f32_16x16x4_f32 v[76:79], v105, v96, v[76:79]
	v_mfma_f32_16x16x4_f32 v[80:83], v105, v97, v[80:83]
	v_mfma_f32_16x16x4_f32 v[84:87], v105, v98, v[84:87]
	v_mfma_f32_16x16x4_f32 v[88:91], v105, v99, v[88:91]
	global_load_dwordx4 v[96:99], v108, s[0:1]
	v_add_u32_e32 v108, 0x2000, v108
	ds_read_b32 v105, v107 offset:5120
	s_waitcnt vmcnt(2) lgkmcnt(2)
	v_mfma_f32_16x16x4_f32 v[76:79], v106, v100, v[76:79]
	v_mfma_f32_16x16x4_f32 v[80:83], v106, v101, v[80:83]
	v_mfma_f32_16x16x4_f32 v[84:87], v106, v102, v[84:87]
	v_mfma_f32_16x16x4_f32 v[88:91], v106, v103, v[88:91]
	global_load_dwordx4 v[100:103], v108, s[0:1]
	v_add_u32_e32 v108, 0x2000, v108
	ds_read_b32 v106, v107 offset:5376
	s_waitcnt vmcnt(2) lgkmcnt(2)
	v_mfma_f32_16x16x4_f32 v[76:79], v104, v92, v[76:79]
	v_mfma_f32_16x16x4_f32 v[80:83], v104, v93, v[80:83]
	v_mfma_f32_16x16x4_f32 v[84:87], v104, v94, v[84:87]
	v_mfma_f32_16x16x4_f32 v[88:91], v104, v95, v[88:91]
	global_load_dwordx4 v[92:95], v108, s[0:1]
	v_add_u32_e32 v108, 0x2000, v108
	ds_read_b32 v104, v107 offset:5632
	s_waitcnt vmcnt(2) lgkmcnt(2)
	v_mfma_f32_16x16x4_f32 v[76:79], v105, v96, v[76:79]
	v_mfma_f32_16x16x4_f32 v[80:83], v105, v97, v[80:83]
	v_mfma_f32_16x16x4_f32 v[84:87], v105, v98, v[84:87]
	v_mfma_f32_16x16x4_f32 v[88:91], v105, v99, v[88:91]
	global_load_dwordx4 v[96:99], v108, s[0:1]
	v_add_u32_e32 v108, 0x2000, v108
	ds_read_b32 v105, v107 offset:5888
	s_waitcnt vmcnt(2) lgkmcnt(2)
	v_mfma_f32_16x16x4_f32 v[76:79], v106, v100, v[76:79]
	v_mfma_f32_16x16x4_f32 v[80:83], v106, v101, v[80:83]
	v_mfma_f32_16x16x4_f32 v[84:87], v106, v102, v[84:87]
	v_mfma_f32_16x16x4_f32 v[88:91], v106, v103, v[88:91]
	global_load_dwordx4 v[100:103], v108, s[0:1]
	v_add_u32_e32 v108, 0x2000, v108
	ds_read_b32 v106, v107 offset:6144
	s_waitcnt vmcnt(2) lgkmcnt(2)
	v_mfma_f32_16x16x4_f32 v[76:79], v104, v92, v[76:79]
	v_mfma_f32_16x16x4_f32 v[80:83], v104, v93, v[80:83]
	v_mfma_f32_16x16x4_f32 v[84:87], v104, v94, v[84:87]
	v_mfma_f32_16x16x4_f32 v[88:91], v104, v95, v[88:91]
	global_load_dwordx4 v[92:95], v108, s[0:1]
	v_add_u32_e32 v108, 0x2000, v108
	ds_read_b32 v104, v107 offset:6400
	s_waitcnt vmcnt(2) lgkmcnt(2)
	v_mfma_f32_16x16x4_f32 v[76:79], v105, v96, v[76:79]
	v_mfma_f32_16x16x4_f32 v[80:83], v105, v97, v[80:83]
	v_mfma_f32_16x16x4_f32 v[84:87], v105, v98, v[84:87]
	v_mfma_f32_16x16x4_f32 v[88:91], v105, v99, v[88:91]
	global_load_dwordx4 v[96:99], v108, s[0:1]
	v_add_u32_e32 v108, 0x2000, v108
	ds_read_b32 v105, v107 offset:6656
	s_waitcnt vmcnt(2) lgkmcnt(2)
	v_mfma_f32_16x16x4_f32 v[76:79], v106, v100, v[76:79]
	v_mfma_f32_16x16x4_f32 v[80:83], v106, v101, v[80:83]
	v_mfma_f32_16x16x4_f32 v[84:87], v106, v102, v[84:87]
	v_mfma_f32_16x16x4_f32 v[88:91], v106, v103, v[88:91]
	global_load_dwordx4 v[100:103], v108, s[0:1]
	v_add_u32_e32 v108, 0x2000, v108
	ds_read_b32 v106, v107 offset:6912
	s_waitcnt vmcnt(2) lgkmcnt(2)
	v_mfma_f32_16x16x4_f32 v[76:79], v104, v92, v[76:79]
	v_mfma_f32_16x16x4_f32 v[80:83], v104, v93, v[80:83]
	v_mfma_f32_16x16x4_f32 v[84:87], v104, v94, v[84:87]
	v_mfma_f32_16x16x4_f32 v[88:91], v104, v95, v[88:91]
	global_load_dwordx4 v[92:95], v108, s[0:1]
	v_add_u32_e32 v108, 0x2000, v108
	ds_read_b32 v104, v107 offset:7168
	s_waitcnt vmcnt(2) lgkmcnt(2)
	v_mfma_f32_16x16x4_f32 v[76:79], v105, v96, v[76:79]
	v_mfma_f32_16x16x4_f32 v[80:83], v105, v97, v[80:83]
	v_mfma_f32_16x16x4_f32 v[84:87], v105, v98, v[84:87]
	v_mfma_f32_16x16x4_f32 v[88:91], v105, v99, v[88:91]
	global_load_dwordx4 v[96:99], v108, s[0:1]
	v_add_u32_e32 v108, 0x2000, v108
	ds_read_b32 v105, v107 offset:7424
	s_waitcnt vmcnt(2) lgkmcnt(2)
	v_mfma_f32_16x16x4_f32 v[76:79], v106, v100, v[76:79]
	v_mfma_f32_16x16x4_f32 v[80:83], v106, v101, v[80:83]
	v_mfma_f32_16x16x4_f32 v[84:87], v106, v102, v[84:87]
	v_mfma_f32_16x16x4_f32 v[88:91], v106, v103, v[88:91]
	global_load_dwordx4 v[100:103], v108, s[0:1]
	v_add_u32_e32 v108, 0x2000, v108
	ds_read_b32 v106, v107 offset:7680
	s_waitcnt vmcnt(2) lgkmcnt(2)
	v_mfma_f32_16x16x4_f32 v[76:79], v104, v92, v[76:79]
	v_mfma_f32_16x16x4_f32 v[80:83], v104, v93, v[80:83]
	v_mfma_f32_16x16x4_f32 v[84:87], v104, v94, v[84:87]
	v_mfma_f32_16x16x4_f32 v[88:91], v104, v95, v[88:91]
	global_load_dwordx4 v[92:95], v108, s[0:1]
	v_add_u32_e32 v108, 0x2000, v108
	ds_read_b32 v104, v107 offset:7936
	s_waitcnt vmcnt(2) lgkmcnt(2)
	v_mfma_f32_16x16x4_f32 v[76:79], v105, v96, v[76:79]
	v_mfma_f32_16x16x4_f32 v[80:83], v105, v97, v[80:83]
	v_mfma_f32_16x16x4_f32 v[84:87], v105, v98, v[84:87]
	v_mfma_f32_16x16x4_f32 v[88:91], v105, v99, v[88:91]
	s_waitcnt vmcnt(1) lgkmcnt(1)
	v_mfma_f32_16x16x4_f32 v[76:79], v106, v100, v[76:79]
	v_mfma_f32_16x16x4_f32 v[80:83], v106, v101, v[80:83]
	v_mfma_f32_16x16x4_f32 v[84:87], v106, v102, v[84:87]
	v_mfma_f32_16x16x4_f32 v[88:91], v106, v103, v[88:91]
	s_waitcnt vmcnt(0) lgkmcnt(0)
	v_mfma_f32_16x16x4_f32 v[76:79], v104, v92, v[76:79]
	v_mfma_f32_16x16x4_f32 v[80:83], v104, v93, v[80:83]
	v_mfma_f32_16x16x4_f32 v[84:87], v104, v94, v[84:87]
	v_mfma_f32_16x16x4_f32 v[88:91], v104, v95, v[88:91]
	s_nop 15
	s_nop 3
	ds_write_b32 v109, v76 offset:8192
	ds_write_b32 v109, v77 offset:8448
	ds_write_b32 v109, v78 offset:8704
	ds_write_b32 v109, v79 offset:8960
	ds_write_b32 v109, v80 offset:8196
	ds_write_b32 v109, v81 offset:8452
	ds_write_b32 v109, v82 offset:8708
	ds_write_b32 v109, v83 offset:8964
	ds_write_b32 v109, v84 offset:8200
	ds_write_b32 v109, v85 offset:8456
	ds_write_b32 v109, v86 offset:8712
	ds_write_b32 v109, v87 offset:8968
	ds_write_b32 v109, v88 offset:8204
	ds_write_b32 v109, v89 offset:8460
	ds_write_b32 v109, v90 offset:8716
	ds_write_b32 v109, v91 offset:8972
	s_waitcnt lgkmcnt(0)
	ds_read2st64_b32 v[62:63], v110 offset0:0 offset1:1
	ds_read2st64_b32 v[56:57], v110 offset0:2 offset1:3
	ds_read2st64_b32 v[50:51], v110 offset0:4 offset1:5
	ds_read2st64_b32 v[44:45], v110 offset0:6 offset1:7
	ds_read2st64_b32 v[38:39], v110 offset0:8 offset1:9
	ds_read2st64_b32 v[32:33], v110 offset0:10 offset1:11
	ds_read2st64_b32 v[26:27], v110 offset0:12 offset1:13
	ds_read2st64_b32 v[20:21], v110 offset0:14 offset1:15
	ds_read2st64_b32 v[64:65], v110 offset0:16 offset1:17
	ds_read2st64_b32 v[58:59], v110 offset0:18 offset1:19
	ds_read2st64_b32 v[52:53], v110 offset0:20 offset1:21
	ds_read2st64_b32 v[46:47], v110 offset0:22 offset1:23
	s_waitcnt lgkmcnt(0)
	ds_read2st64_b32 v[40:41], v110 offset0:24 offset1:25
	ds_read2st64_b32 v[34:35], v110 offset0:26 offset1:27
	ds_read2st64_b32 v[28:29], v110 offset0:28 offset1:29
	ds_read2st64_b32 v[22:23], v110 offset0:30 offset1:31
	ds_read2st64_b32 v[66:67], v110 offset0:32 offset1:33
	ds_read2st64_b32 v[60:61], v110 offset0:34 offset1:35
	ds_read2st64_b32 v[54:55], v110 offset0:36 offset1:37
	ds_read2st64_b32 v[48:49], v110 offset0:38 offset1:39
	ds_read2st64_b32 v[42:43], v110 offset0:40 offset1:41
	ds_read2st64_b32 v[36:37], v110 offset0:42 offset1:43
	ds_read2st64_b32 v[30:31], v110 offset0:44 offset1:45
	ds_read2st64_b32 v[24:25], v110 offset0:46 offset1:47
	s_waitcnt lgkmcnt(0)
	s_waitcnt lgkmcnt(0)
	s_ashr_i32 s19, s18, 31
	s_lshl_b64 s[0:1], s[18:19], 10
	v_lshlrev_b32_e32 v78, 1, v164
	v_or_b32_e32 v74, s0, v78
	v_mov_b32_e32 v75, s1
	s_or_b32 s0, s18, 1
	v_cvt_pk_bf16_f32 v17, v62, v1
	v_lshl_add_u64 v[76:77], s[12:13], 0, v[74:75]
	s_ashr_i32 s1, s0, 31
	global_store_short v[76:77], v17, off
	v_cvt_pk_bf16_f32 v17, v64, v1
	v_lshl_add_u64 v[76:77], s[14:15], 0, v[74:75]
	v_lshl_add_u64 v[74:75], s[92:93], 0, v[74:75]
	s_lshl_b64 s[0:1], s[0:1], 9
	global_store_short v[76:77], v17, off
	v_cvt_pk_bf16_f32 v17, v66, v1
	global_store_short v[74:75], v17, off
	v_lshl_add_u64 v[74:75], s[0:1], 0, v[164:165]
	v_cvt_pk_bf16_f32 v17, v63, v1
	v_lshlrev_b64 v[62:63], 1, v[74:75]
	s_or_b32 s0, s18, 2
	v_lshl_add_u64 v[74:75], s[12:13], 0, v[62:63]
	s_ashr_i32 s1, s0, 31
	global_store_short v[74:75], v17, off
	v_cvt_pk_bf16_f32 v17, v65, v1
	v_lshl_add_u64 v[64:65], s[14:15], 0, v[62:63]
	v_lshl_add_u64 v[62:63], s[92:93], 0, v[62:63]
	s_lshl_b64 s[0:1], s[0:1], 10
	global_store_short v[64:65], v17, off
	v_cvt_pk_bf16_f32 v17, v67, v1
	global_store_short v[62:63], v17, off
	v_or_b32_e32 v62, s0, v78
	v_mov_b32_e32 v63, s1
	s_or_b32 s0, s18, 3
	v_cvt_pk_bf16_f32 v17, v56, v1
	v_lshl_add_u64 v[64:65], s[12:13], 0, v[62:63]
	s_ashr_i32 s1, s0, 31
	global_store_short v[64:65], v17, off
	v_cvt_pk_bf16_f32 v17, v58, v1
	v_lshl_add_u64 v[64:65], s[14:15], 0, v[62:63]
	v_lshl_add_u64 v[62:63], s[92:93], 0, v[62:63]
	s_lshl_b64 s[0:1], s[0:1], 9
	global_store_short v[64:65], v17, off
	v_cvt_pk_bf16_f32 v17, v60, v1
	global_store_short v[62:63], v17, off
	v_lshl_add_u64 v[62:63], s[0:1], 0, v[164:165]
	v_cvt_pk_bf16_f32 v17, v57, v1
	v_lshlrev_b64 v[56:57], 1, v[62:63]
	s_or_b32 s0, s18, 4
	v_lshl_add_u64 v[62:63], s[12:13], 0, v[56:57]
	s_ashr_i32 s1, s0, 31
	global_store_short v[62:63], v17, off
	v_cvt_pk_bf16_f32 v17, v59, v1
	v_lshl_add_u64 v[58:59], s[14:15], 0, v[56:57]
	v_lshl_add_u64 v[56:57], s[92:93], 0, v[56:57]
	s_lshl_b64 s[0:1], s[0:1], 10
	global_store_short v[58:59], v17, off
	v_cvt_pk_bf16_f32 v17, v61, v1
	global_store_short v[56:57], v17, off
	v_or_b32_e32 v56, s0, v78
	v_mov_b32_e32 v57, s1
	s_or_b32 s0, s18, 5
	v_cvt_pk_bf16_f32 v17, v50, v1
	v_lshl_add_u64 v[58:59], s[12:13], 0, v[56:57]
	s_ashr_i32 s1, s0, 31
	global_store_short v[58:59], v17, off
	v_cvt_pk_bf16_f32 v17, v52, v1
	v_lshl_add_u64 v[58:59], s[14:15], 0, v[56:57]
	v_lshl_add_u64 v[56:57], s[92:93], 0, v[56:57]
	s_lshl_b64 s[0:1], s[0:1], 9
	global_store_short v[58:59], v17, off
	v_cvt_pk_bf16_f32 v17, v54, v1
	global_store_short v[56:57], v17, off
	v_lshl_add_u64 v[56:57], s[0:1], 0, v[164:165]
	v_cvt_pk_bf16_f32 v17, v51, v1
	v_lshlrev_b64 v[50:51], 1, v[56:57]
	s_or_b32 s0, s18, 6
	v_lshl_add_u64 v[56:57], s[12:13], 0, v[50:51]
	s_ashr_i32 s1, s0, 31
	global_store_short v[56:57], v17, off
	v_cvt_pk_bf16_f32 v17, v53, v1
	v_lshl_add_u64 v[52:53], s[14:15], 0, v[50:51]
	v_lshl_add_u64 v[50:51], s[92:93], 0, v[50:51]
	s_lshl_b64 s[0:1], s[0:1], 10
	global_store_short v[52:53], v17, off
	v_cvt_pk_bf16_f32 v17, v55, v1
	global_store_short v[50:51], v17, off
	v_or_b32_e32 v50, s0, v78
	v_mov_b32_e32 v51, s1
	s_or_b32 s0, s18, 7
	v_cvt_pk_bf16_f32 v17, v44, v1
	v_lshl_add_u64 v[52:53], s[12:13], 0, v[50:51]
	s_ashr_i32 s1, s0, 31
	global_store_short v[52:53], v17, off
	v_cvt_pk_bf16_f32 v17, v46, v1
	v_lshl_add_u64 v[52:53], s[14:15], 0, v[50:51]
	v_lshl_add_u64 v[50:51], s[92:93], 0, v[50:51]
	s_lshl_b64 s[0:1], s[0:1], 9
	global_store_short v[52:53], v17, off
	v_cvt_pk_bf16_f32 v17, v48, v1
	global_store_short v[50:51], v17, off
	v_lshl_add_u64 v[50:51], s[0:1], 0, v[164:165]
	v_cvt_pk_bf16_f32 v17, v45, v1
	v_lshlrev_b64 v[44:45], 1, v[50:51]
	s_or_b32 s0, s18, 8
	v_lshl_add_u64 v[50:51], s[12:13], 0, v[44:45]
	s_ashr_i32 s1, s0, 31
	global_store_short v[50:51], v17, off
	v_cvt_pk_bf16_f32 v17, v47, v1
	v_lshl_add_u64 v[46:47], s[14:15], 0, v[44:45]
	v_lshl_add_u64 v[44:45], s[92:93], 0, v[44:45]
	s_lshl_b64 s[0:1], s[0:1], 10
	global_store_short v[46:47], v17, off
	v_cvt_pk_bf16_f32 v17, v49, v1
	global_store_short v[44:45], v17, off
	v_or_b32_e32 v44, s0, v78
	v_mov_b32_e32 v45, s1
	s_or_b32 s0, s18, 9
	v_cvt_pk_bf16_f32 v17, v38, v1
	v_lshl_add_u64 v[46:47], s[12:13], 0, v[44:45]
	s_ashr_i32 s1, s0, 31
	global_store_short v[46:47], v17, off
	v_cvt_pk_bf16_f32 v17, v40, v1
	v_lshl_add_u64 v[46:47], s[14:15], 0, v[44:45]
	v_lshl_add_u64 v[44:45], s[92:93], 0, v[44:45]
	s_lshl_b64 s[0:1], s[0:1], 9
	global_store_short v[46:47], v17, off
	v_cvt_pk_bf16_f32 v17, v42, v1
	global_store_short v[44:45], v17, off
	v_lshl_add_u64 v[44:45], s[0:1], 0, v[164:165]
	v_cvt_pk_bf16_f32 v17, v39, v1
	v_lshlrev_b64 v[38:39], 1, v[44:45]
	s_or_b32 s0, s18, 10
	v_lshl_add_u64 v[44:45], s[12:13], 0, v[38:39]
	s_ashr_i32 s1, s0, 31
	global_store_short v[44:45], v17, off
	v_cvt_pk_bf16_f32 v17, v41, v1
	v_lshl_add_u64 v[40:41], s[14:15], 0, v[38:39]
	v_lshl_add_u64 v[38:39], s[92:93], 0, v[38:39]
	s_lshl_b64 s[0:1], s[0:1], 10
	global_store_short v[40:41], v17, off
	v_cvt_pk_bf16_f32 v17, v43, v1
	global_store_short v[38:39], v17, off
	v_or_b32_e32 v38, s0, v78
	v_mov_b32_e32 v39, s1
	s_or_b32 s0, s18, 11
	v_cvt_pk_bf16_f32 v17, v32, v1
	v_lshl_add_u64 v[40:41], s[12:13], 0, v[38:39]
	s_ashr_i32 s1, s0, 31
	global_store_short v[40:41], v17, off
	v_cvt_pk_bf16_f32 v17, v34, v1
	v_lshl_add_u64 v[40:41], s[14:15], 0, v[38:39]
	v_lshl_add_u64 v[38:39], s[92:93], 0, v[38:39]
	s_lshl_b64 s[0:1], s[0:1], 9
	global_store_short v[40:41], v17, off
	v_cvt_pk_bf16_f32 v17, v36, v1
	global_store_short v[38:39], v17, off
	v_lshl_add_u64 v[38:39], s[0:1], 0, v[164:165]
	v_cvt_pk_bf16_f32 v17, v33, v1
	v_lshlrev_b64 v[32:33], 1, v[38:39]
	s_or_b32 s0, s18, 12
	v_lshl_add_u64 v[38:39], s[12:13], 0, v[32:33]
	s_ashr_i32 s1, s0, 31
	global_store_short v[38:39], v17, off
	v_cvt_pk_bf16_f32 v17, v35, v1
	v_lshl_add_u64 v[34:35], s[14:15], 0, v[32:33]
	v_lshl_add_u64 v[32:33], s[92:93], 0, v[32:33]
	s_lshl_b64 s[0:1], s[0:1], 10
	global_store_short v[34:35], v17, off
	v_cvt_pk_bf16_f32 v17, v37, v1
	global_store_short v[32:33], v17, off
	v_or_b32_e32 v32, s0, v78
	v_mov_b32_e32 v33, s1
	s_or_b32 s0, s18, 13
	v_cvt_pk_bf16_f32 v17, v26, v1
	v_lshl_add_u64 v[34:35], s[12:13], 0, v[32:33]
	s_ashr_i32 s1, s0, 31
	global_store_short v[34:35], v17, off
	v_cvt_pk_bf16_f32 v17, v28, v1
	v_lshl_add_u64 v[34:35], s[14:15], 0, v[32:33]
	v_lshl_add_u64 v[32:33], s[92:93], 0, v[32:33]
	s_lshl_b64 s[0:1], s[0:1], 9
	global_store_short v[34:35], v17, off
	v_cvt_pk_bf16_f32 v17, v30, v1
	global_store_short v[32:33], v17, off
	v_lshl_add_u64 v[32:33], s[0:1], 0, v[164:165]
	v_cvt_pk_bf16_f32 v17, v27, v1
	v_lshlrev_b64 v[26:27], 1, v[32:33]
	s_or_b32 s0, s18, 14
	v_lshl_add_u64 v[32:33], s[12:13], 0, v[26:27]
	s_ashr_i32 s1, s0, 31
	global_store_short v[32:33], v17, off
	v_cvt_pk_bf16_f32 v17, v29, v1
	v_lshl_add_u64 v[28:29], s[14:15], 0, v[26:27]
	v_lshl_add_u64 v[26:27], s[92:93], 0, v[26:27]
	s_lshl_b64 s[0:1], s[0:1], 10
	global_store_short v[28:29], v17, off
	v_cvt_pk_bf16_f32 v17, v31, v1
	global_store_short v[26:27], v17, off
	v_or_b32_e32 v26, s0, v78
	v_mov_b32_e32 v27, s1
	s_or_b32 s0, s18, 15
	v_cvt_pk_bf16_f32 v17, v20, v1
	v_lshl_add_u64 v[28:29], s[12:13], 0, v[26:27]
	s_ashr_i32 s1, s0, 31
	global_store_short v[28:29], v17, off
	v_cvt_pk_bf16_f32 v17, v22, v1
	v_lshl_add_u64 v[28:29], s[14:15], 0, v[26:27]
	v_lshl_add_u64 v[26:27], s[92:93], 0, v[26:27]
	s_lshl_b64 s[0:1], s[0:1], 9
	global_store_short v[28:29], v17, off
	v_cvt_pk_bf16_f32 v17, v24, v1
	global_store_short v[26:27], v17, off
	v_lshl_add_u64 v[26:27], s[0:1], 0, v[164:165]
	v_cvt_pk_bf16_f32 v17, v21, v1
	v_lshlrev_b64 v[20:21], 1, v[26:27]
	v_lshl_add_u64 v[26:27], s[12:13], 0, v[20:21]
	s_add_i32 s48, s48, s30
	global_store_short v[26:27], v17, off
	v_cvt_pk_bf16_f32 v17, v23, v1
	v_lshl_add_u64 v[22:23], s[14:15], 0, v[20:21]
	v_lshl_add_u64 v[20:21], s[92:93], 0, v[20:21]
	s_cmpk_gt_i32 s48, 0x3ff
	global_store_short v[22:23], v17, off
	v_cvt_pk_bf16_f32 v17, v25, v1
	global_store_short v[20:21], v17, off
	s_barrier
	s_cbranch_scc0 .LBB0_944

.LBB0_1087:
	s_andn2_saveexec_b64 s[16:17], s[12:13]
	s_cbranch_execz .LBB0_1111
	s_lshr_b32 s10, s2, 6
	s_bfe_u32 s11, s2, 0x20004
	s_bfe_u32 s14, s2, 0x20002
	s_and_b32 s15, s2, 3
	s_add_u32 s20, s28, 0x3400000
	s_addc_u32 s21, s29, 0
	s_mov_b32 s46, 0x22000
	s_mov_b32 s47, 0
	s_mov_b32 s55, 1
	s_lshl_b32 s56, s11, 12
	s_cmp_eq_u32 s10, 0
	s_cbranch_scc1 .Lhs_fwd
	s_mov_b32 s46, 0xfffde000
	s_mov_b32 s47, -1
	s_mov_b32 s55, -1
	s_add_u32 s56, s56, 0xfff
.Lhs_fwd:
	s_movk_i32 s35, 0x2200
	s_lshl_b32 s58, s14, 7
	s_lshl_b32 s57, s10, 9
	s_add_u32 s57, s57, 0x200
	s_lshl_b32 s59, s15, 5
	s_add_u32 s59, s59, 0x600
	v_readlane_b32 s44, v255, 19
	v_readlane_b32 s45, v255, 20
	v_and_b32_e32 v100, 15, v164
	v_bfe_u32 v101, v164, 4, 4
	v_cmp_gt_u32_e64 s[48:49], 4, v100
	v_mul_lo_u32 v102, v101, s55
	v_add_u32_e32 v102, s56, v102
	v_mul_lo_u32 v102, v102, s35
	v_lshl_add_u32 v103, v100, 3, s58
	v_lshl_add_u32 v102, v103, 1, v102
	v_mov_b32_e32 v103, 0
	v_lshl_add_u64 v[76:77], v[102:103], 0, s[20:21]
	s_lshl_b32 s57, s57, 1
	s_lshl_b32 s59, s59, 1
	s_mov_b32 s60, s57
	s_mov_b32 s61, 0
	v_lshl_add_u64 v[78:79], v[76:77], 0, s[60:61]
	s_mov_b32 s60, s59
	v_lshl_add_u64 v[80:81], v[76:77], 0, s[60:61]
	v_mul_u32_u24_e32 v82, 0x420, v101
	v_lshl_add_u32 v82, v100, 5, v82
	v_lshrrev_b32_e32 v104, 3, v100
	v_lshl_add_u32 v82, v104, 4, v82
	v_lshlrev_b32_e32 v83, 7, v101
	v_lshl_add_u32 v83, v100, 5, v83
	v_add_u32_e32 v83, 0x8400, v83
	v_lshl_add_u32 v105, v100, 3, s58
	v_lshlrev_b32_e32 v105, 2, v105
	global_load_dwordx4 v[36:39], v105, s[44:45]
	global_load_dwordx4 v[40:43], v105, s[44:45] offset:16
	global_load_dwordx4 v[44:47], v105, s[44:45] offset:2048
	global_load_dwordx4 v[48:51], v105, s[44:45] offset:2064
	global_load_dwordx4 v[0:3], v[76:77], off
	global_load_dwordx4 v[4:7], v[78:79], off
	s_mov_b64 exec, s[48:49]
	global_load_dwordx4 v[8:11], v[80:81], off
	s_mov_b64 exec, -1
	v_lshl_add_u64 v[76:77], v[76:77], 0, s[46:47]
	v_lshl_add_u64 v[78:79], v[78:79], 0, s[46:47]
	v_lshl_add_u64 v[80:81], v[80:81], 0, s[46:47]
	global_load_dwordx4 v[12:15], v[76:77], off
	global_load_dwordx4 v[16:19], v[78:79], off
	s_mov_b64 exec, s[48:49]
	global_load_dwordx4 v[20:23], v[80:81], off
	s_mov_b64 exec, -1
	v_lshl_add_u64 v[76:77], v[76:77], 0, s[46:47]
	v_lshl_add_u64 v[78:79], v[78:79], 0, s[46:47]
	v_lshl_add_u64 v[80:81], v[80:81], 0, s[46:47]
	global_load_dwordx4 v[24:27], v[76:77], off
	global_load_dwordx4 v[28:31], v[78:79], off
	s_mov_b64 exec, s[48:49]
	global_load_dwordx4 v[32:35], v[80:81], off
	s_mov_b64 exec, -1
	v_lshl_add_u64 v[76:77], v[76:77], 0, s[46:47]
	v_lshl_add_u64 v[78:79], v[78:79], 0, s[46:47]
	v_lshl_add_u64 v[80:81], v[80:81], 0, s[46:47]
	s_waitcnt vmcnt(9)
	v_sub_f32_e32 v52, v36, v44
	v_sub_f32_e32 v53, v37, v45
	v_sub_f32_e32 v54, v38, v46
	v_sub_f32_e32 v55, v39, v47
	v_sub_f32_e32 v56, v40, v48
	v_sub_f32_e32 v57, v41, v49
	v_sub_f32_e32 v58, v42, v50
	v_sub_f32_e32 v59, v43, v51
	v_mul_f32_e32 v52, 0x3fb8aa3b, v52
	v_mul_f32_e32 v53, 0x3fb8aa3b, v53
	v_mul_f32_e32 v54, 0x3fb8aa3b, v54
	v_mul_f32_e32 v55, 0x3fb8aa3b, v55
	v_mul_f32_e32 v56, 0x3fb8aa3b, v56
	v_mul_f32_e32 v57, 0x3fb8aa3b, v57
	v_mul_f32_e32 v58, 0x3fb8aa3b, v58
	v_mul_f32_e32 v59, 0x3fb8aa3b, v59
	v_exp_f32_e32 v52, v52
	v_exp_f32_e32 v53, v53
	v_exp_f32_e32 v54, v54
	v_exp_f32_e32 v55, v55
	v_exp_f32_e32 v56, v56
	v_exp_f32_e32 v57, v57
	v_exp_f32_e32 v58, v58
	v_exp_f32_e32 v59, v59
	v_add_f32_e32 v52, 1.0, v52
	v_add_f32_e32 v53, 1.0, v53
	v_add_f32_e32 v54, 1.0, v54
	v_add_f32_e32 v55, 1.0, v55
	v_add_f32_e32 v56, 1.0, v56
	v_add_f32_e32 v57, 1.0, v57
	v_add_f32_e32 v58, 1.0, v58
	v_add_f32_e32 v59, 1.0, v59
	v_rcp_f32_e32 v84, v52
	v_rcp_f32_e32 v85, v53
	v_rcp_f32_e32 v86, v54
	v_rcp_f32_e32 v87, v55
	v_rcp_f32_e32 v88, v56
	v_rcp_f32_e32 v89, v57
	v_rcp_f32_e32 v90, v58
	v_rcp_f32_e32 v91, v59
	v_sub_f32_e32 v92, 1.0, v84
	v_sub_f32_e32 v93, 1.0, v85
	v_sub_f32_e32 v94, 1.0, v86
	v_sub_f32_e32 v95, 1.0, v87
	v_sub_f32_e32 v96, 1.0, v88
	v_sub_f32_e32 v97, 1.0, v89
	v_sub_f32_e32 v98, 1.0, v90
	v_sub_f32_e32 v99, 1.0, v91
	s_waitcnt vmcnt(6)
	v_lshlrev_b32_e32 v36, 16, v0
	v_and_b32_e32 v37, 0xffff0000, v0
	v_lshlrev_b32_e32 v38, 16, v1
	v_and_b32_e32 v39, 0xffff0000, v1
	v_lshlrev_b32_e32 v40, 16, v2
	v_and_b32_e32 v41, 0xffff0000, v2
	v_lshlrev_b32_e32 v42, 16, v3
	v_and_b32_e32 v43, 0xffff0000, v3
	v_lshlrev_b32_e32 v44, 16, v4
	v_and_b32_e32 v45, 0xffff0000, v4
	v_lshlrev_b32_e32 v46, 16, v5
	v_and_b32_e32 v47, 0xffff0000, v5
	v_lshlrev_b32_e32 v48, 16, v6
	v_and_b32_e32 v49, 0xffff0000, v6
	v_lshlrev_b32_e32 v50, 16, v7
	v_and_b32_e32 v51, 0xffff0000, v7
	v_mul_f32_e32 v52, 0xbfb8aa3b, v36
	v_mul_f32_e32 v53, 0xbfb8aa3b, v37
	v_mul_f32_e32 v54, 0xbfb8aa3b, v38
	v_mul_f32_e32 v55, 0xbfb8aa3b, v39
	v_mul_f32_e32 v56, 0xbfb8aa3b, v40
	v_mul_f32_e32 v57, 0xbfb8aa3b, v41
	v_mul_f32_e32 v58, 0xbfb8aa3b, v42
	v_mul_f32_e32 v59, 0xbfb8aa3b, v43
	v_mul_f32_e32 v60, 0xbfb8aa3b, v44
	v_mul_f32_e32 v61, 0xbfb8aa3b, v45
	v_mul_f32_e32 v62, 0xbfb8aa3b, v46
	v_mul_f32_e32 v63, 0xbfb8aa3b, v47
	v_mul_f32_e32 v64, 0xbfb8aa3b, v48
	v_mul_f32_e32 v65, 0xbfb8aa3b, v49
	v_mul_f32_e32 v66, 0xbfb8aa3b, v50
	v_mul_f32_e32 v67, 0xbfb8aa3b, v51
	v_exp_f32_e32 v52, v52
	v_exp_f32_e32 v53, v53
	v_exp_f32_e32 v54, v54
	v_exp_f32_e32 v55, v55
	v_exp_f32_e32 v56, v56
	v_exp_f32_e32 v57, v57
	v_exp_f32_e32 v58, v58
	v_exp_f32_e32 v59, v59
	v_exp_f32_e32 v60, v60
	v_exp_f32_e32 v61, v61
	v_exp_f32_e32 v62, v62
	v_exp_f32_e32 v63, v63
	v_exp_f32_e32 v64, v64
	v_exp_f32_e32 v65, v65
	v_exp_f32_e32 v66, v66
	v_exp_f32_e32 v67, v67
	v_add_f32_e32 v52, 1.0, v52
	v_add_f32_e32 v53, 1.0, v53
	v_add_f32_e32 v54, 1.0, v54
	v_add_f32_e32 v55, 1.0, v55
	v_add_f32_e32 v56, 1.0, v56
	v_add_f32_e32 v57, 1.0, v57
	v_add_f32_e32 v58, 1.0, v58
	v_add_f32_e32 v59, 1.0, v59
	v_add_f32_e32 v60, 1.0, v60
	v_add_f32_e32 v61, 1.0, v61
	v_add_f32_e32 v62, 1.0, v62
	v_add_f32_e32 v63, 1.0, v63
	v_add_f32_e32 v64, 1.0, v64
	v_add_f32_e32 v65, 1.0, v65
	v_add_f32_e32 v66, 1.0, v66
	v_add_f32_e32 v67, 1.0, v67
	v_rcp_f32_e32 v52, v52
	v_rcp_f32_e32 v53, v53
	v_rcp_f32_e32 v54, v54
	v_rcp_f32_e32 v55, v55
	v_rcp_f32_e32 v56, v56
	v_rcp_f32_e32 v57, v57
	v_rcp_f32_e32 v58, v58
	v_rcp_f32_e32 v59, v59
	v_rcp_f32_e32 v60, v60
	v_rcp_f32_e32 v61, v61
	v_rcp_f32_e32 v62, v62
	v_rcp_f32_e32 v63, v63
	v_rcp_f32_e32 v64, v64
	v_rcp_f32_e32 v65, v65
	v_rcp_f32_e32 v66, v66
	v_rcp_f32_e32 v67, v67
	v_mul_f32_e32 v36, v36, v52
	v_mul_f32_e32 v37, v37, v53
	v_mul_f32_e32 v38, v38, v54
	v_mul_f32_e32 v39, v39, v55
	v_mul_f32_e32 v40, v40, v56
	v_mul_f32_e32 v41, v41, v57
	v_mul_f32_e32 v42, v42, v58
	v_mul_f32_e32 v43, v43, v59
	v_fma_f32 v44, v92, v60, v84
	v_fma_f32 v45, v93, v61, v85
	v_fma_f32 v46, v94, v62, v86
	v_fma_f32 v47, v95, v63, v87
	v_fma_f32 v48, v96, v64, v88
	v_fma_f32 v49, v97, v65, v89
	v_fma_f32 v50, v98, v66, v90
	v_fma_f32 v51, v99, v67, v91
	v_lshlrev_b32_e32 v68, 16, v8
	v_and_b32_e32 v69, 0xffff0000, v8
	v_lshlrev_b32_e32 v70, 16, v9
	v_and_b32_e32 v71, 0xffff0000, v9
	v_lshlrev_b32_e32 v72, 16, v10
	v_and_b32_e32 v73, 0xffff0000, v10
	v_lshlrev_b32_e32 v74, 16, v11
	v_and_b32_e32 v75, 0xffff0000, v11
	ds_write_b128 v82, v[44:47] offset:0
	ds_write_b128 v82, v[48:51] offset:16
	ds_write_b128 v82, v[36:39] offset:528
	ds_write_b128 v82, v[40:43] offset:544
	s_mov_b64 exec, s[48:49]
	ds_write_b128 v83, v[68:71] offset:0
	ds_write_b128 v83, v[72:75] offset:16
	s_mov_b64 exec, -1
	global_load_dwordx4 v[0:3], v[76:77], off
	global_load_dwordx4 v[4:7], v[78:79], off
	s_mov_b64 exec, s[48:49]
	global_load_dwordx4 v[8:11], v[80:81], off
	s_mov_b64 exec, -1
	v_lshl_add_u64 v[76:77], v[76:77], 0, s[46:47]
	v_lshl_add_u64 v[78:79], v[78:79], 0, s[46:47]
	v_lshl_add_u64 v[80:81], v[80:81], 0, s[46:47]
	s_waitcnt lgkmcnt(0)
	s_barrier
	s_mov_b32 s50, 0
.Lhs_loop:
	s_waitcnt vmcnt(6)
	v_lshlrev_b32_e32 v36, 16, v12
	v_and_b32_e32 v37, 0xffff0000, v12
	v_lshlrev_b32_e32 v38, 16, v13
	v_and_b32_e32 v39, 0xffff0000, v13
	v_lshlrev_b32_e32 v40, 16, v14
	v_and_b32_e32 v41, 0xffff0000, v14
	v_lshlrev_b32_e32 v42, 16, v15
	v_and_b32_e32 v43, 0xffff0000, v15
	v_lshlrev_b32_e32 v44, 16, v16
	v_and_b32_e32 v45, 0xffff0000, v16
	v_lshlrev_b32_e32 v46, 16, v17
	v_and_b32_e32 v47, 0xffff0000, v17
	v_lshlrev_b32_e32 v48, 16, v18
	v_and_b32_e32 v49, 0xffff0000, v18
	v_lshlrev_b32_e32 v50, 16, v19
	v_and_b32_e32 v51, 0xffff0000, v19
	v_mul_f32_e32 v52, 0xbfb8aa3b, v36
	v_mul_f32_e32 v53, 0xbfb8aa3b, v37
	v_mul_f32_e32 v54, 0xbfb8aa3b, v38
	v_mul_f32_e32 v55, 0xbfb8aa3b, v39
	v_mul_f32_e32 v56, 0xbfb8aa3b, v40
	v_mul_f32_e32 v57, 0xbfb8aa3b, v41
	v_mul_f32_e32 v58, 0xbfb8aa3b, v42
	v_mul_f32_e32 v59, 0xbfb8aa3b, v43
	v_mul_f32_e32 v60, 0xbfb8aa3b, v44
	v_mul_f32_e32 v61, 0xbfb8aa3b, v45
	v_mul_f32_e32 v62, 0xbfb8aa3b, v46
	v_mul_f32_e32 v63, 0xbfb8aa3b, v47
	v_mul_f32_e32 v64, 0xbfb8aa3b, v48
	v_mul_f32_e32 v65, 0xbfb8aa3b, v49
	v_mul_f32_e32 v66, 0xbfb8aa3b, v50
	v_mul_f32_e32 v67, 0xbfb8aa3b, v51
	v_exp_f32_e32 v52, v52
	v_exp_f32_e32 v53, v53
	v_exp_f32_e32 v54, v54
	v_exp_f32_e32 v55, v55
	v_exp_f32_e32 v56, v56
	v_exp_f32_e32 v57, v57
	v_exp_f32_e32 v58, v58
	v_exp_f32_e32 v59, v59
	v_exp_f32_e32 v60, v60
	v_exp_f32_e32 v61, v61
	v_exp_f32_e32 v62, v62
	v_exp_f32_e32 v63, v63
	v_exp_f32_e32 v64, v64
	v_exp_f32_e32 v65, v65
	v_exp_f32_e32 v66, v66
	v_exp_f32_e32 v67, v67
	v_add_f32_e32 v52, 1.0, v52
	v_add_f32_e32 v53, 1.0, v53
	v_add_f32_e32 v54, 1.0, v54
	v_add_f32_e32 v55, 1.0, v55
	v_add_f32_e32 v56, 1.0, v56
	v_add_f32_e32 v57, 1.0, v57
	v_add_f32_e32 v58, 1.0, v58
	v_add_f32_e32 v59, 1.0, v59
	v_add_f32_e32 v60, 1.0, v60
	v_add_f32_e32 v61, 1.0, v61
	v_add_f32_e32 v62, 1.0, v62
	v_add_f32_e32 v63, 1.0, v63
	v_add_f32_e32 v64, 1.0, v64
	v_add_f32_e32 v65, 1.0, v65
	v_add_f32_e32 v66, 1.0, v66
	v_add_f32_e32 v67, 1.0, v67
	v_rcp_f32_e32 v52, v52
	v_rcp_f32_e32 v53, v53
	v_rcp_f32_e32 v54, v54
	v_rcp_f32_e32 v55, v55
	v_rcp_f32_e32 v56, v56
	v_rcp_f32_e32 v57, v57
	v_rcp_f32_e32 v58, v58
	v_rcp_f32_e32 v59, v59
	v_rcp_f32_e32 v60, v60
	v_rcp_f32_e32 v61, v61
	v_rcp_f32_e32 v62, v62
	v_rcp_f32_e32 v63, v63
	v_rcp_f32_e32 v64, v64
	v_rcp_f32_e32 v65, v65
	v_rcp_f32_e32 v66, v66
	v_rcp_f32_e32 v67, v67
	v_mul_f32_e32 v36, v36, v52
	v_mul_f32_e32 v37, v37, v53
	v_mul_f32_e32 v38, v38, v54
	v_mul_f32_e32 v39, v39, v55
	v_mul_f32_e32 v40, v40, v56
	v_mul_f32_e32 v41, v41, v57
	v_mul_f32_e32 v42, v42, v58
	v_mul_f32_e32 v43, v43, v59
	v_fma_f32 v44, v92, v60, v84
	v_fma_f32 v45, v93, v61, v85
	v_fma_f32 v46, v94, v62, v86
	v_fma_f32 v47, v95, v63, v87
	v_fma_f32 v48, v96, v64, v88
	v_fma_f32 v49, v97, v65, v89
	v_fma_f32 v50, v98, v66, v90
	v_fma_f32 v51, v99, v67, v91
	v_lshlrev_b32_e32 v68, 16, v20
	v_and_b32_e32 v69, 0xffff0000, v20
	v_lshlrev_b32_e32 v70, 16, v21
	v_and_b32_e32 v71, 0xffff0000, v21
	v_lshlrev_b32_e32 v72, 16, v22
	v_and_b32_e32 v73, 0xffff0000, v22
	v_lshlrev_b32_e32 v74, 16, v23
	v_and_b32_e32 v75, 0xffff0000, v23
	ds_write_b128 v82, v[44:47] offset:16896
	ds_write_b128 v82, v[48:51] offset:16912
	ds_write_b128 v82, v[36:39] offset:17424
	ds_write_b128 v82, v[40:43] offset:17440
	s_mov_b64 exec, s[48:49]
	ds_write_b128 v83, v[68:71] offset:2048
	ds_write_b128 v83, v[72:75] offset:2064
	s_mov_b64 exec, -1
	global_load_dwordx4 v[12:15], v[76:77], off
	global_load_dwordx4 v[16:19], v[78:79], off
	s_mov_b64 exec, s[48:49]
	global_load_dwordx4 v[20:23], v[80:81], off
	s_mov_b64 exec, -1
	v_lshl_add_u64 v[76:77], v[76:77], 0, s[46:47]
	v_lshl_add_u64 v[78:79], v[78:79], 0, s[46:47]
	v_lshl_add_u64 v[80:81], v[80:81], 0, s[46:47]
	s_waitcnt lgkmcnt(0)
	s_barrier
	s_waitcnt vmcnt(6)
	v_lshlrev_b32_e32 v36, 16, v24
	v_and_b32_e32 v37, 0xffff0000, v24
	v_lshlrev_b32_e32 v38, 16, v25
	v_and_b32_e32 v39, 0xffff0000, v25
	v_lshlrev_b32_e32 v40, 16, v26
	v_and_b32_e32 v41, 0xffff0000, v26
	v_lshlrev_b32_e32 v42, 16, v27
	v_and_b32_e32 v43, 0xffff0000, v27
	v_lshlrev_b32_e32 v44, 16, v28
	v_and_b32_e32 v45, 0xffff0000, v28
	v_lshlrev_b32_e32 v46, 16, v29
	v_and_b32_e32 v47, 0xffff0000, v29
	v_lshlrev_b32_e32 v48, 16, v30
	v_and_b32_e32 v49, 0xffff0000, v30
	v_lshlrev_b32_e32 v50, 16, v31
	v_and_b32_e32 v51, 0xffff0000, v31
	v_mul_f32_e32 v52, 0xbfb8aa3b, v36
	v_mul_f32_e32 v53, 0xbfb8aa3b, v37
	v_mul_f32_e32 v54, 0xbfb8aa3b, v38
	v_mul_f32_e32 v55, 0xbfb8aa3b, v39
	v_mul_f32_e32 v56, 0xbfb8aa3b, v40
	v_mul_f32_e32 v57, 0xbfb8aa3b, v41
	v_mul_f32_e32 v58, 0xbfb8aa3b, v42
	v_mul_f32_e32 v59, 0xbfb8aa3b, v43
	v_mul_f32_e32 v60, 0xbfb8aa3b, v44
	v_mul_f32_e32 v61, 0xbfb8aa3b, v45
	v_mul_f32_e32 v62, 0xbfb8aa3b, v46
	v_mul_f32_e32 v63, 0xbfb8aa3b, v47
	v_mul_f32_e32 v64, 0xbfb8aa3b, v48
	v_mul_f32_e32 v65, 0xbfb8aa3b, v49
	v_mul_f32_e32 v66, 0xbfb8aa3b, v50
	v_mul_f32_e32 v67, 0xbfb8aa3b, v51
	v_exp_f32_e32 v52, v52
	v_exp_f32_e32 v53, v53
	v_exp_f32_e32 v54, v54
	v_exp_f32_e32 v55, v55
	v_exp_f32_e32 v56, v56
	v_exp_f32_e32 v57, v57
	v_exp_f32_e32 v58, v58
	v_exp_f32_e32 v59, v59
	v_exp_f32_e32 v60, v60
	v_exp_f32_e32 v61, v61
	v_exp_f32_e32 v62, v62
	v_exp_f32_e32 v63, v63
	v_exp_f32_e32 v64, v64
	v_exp_f32_e32 v65, v65
	v_exp_f32_e32 v66, v66
	v_exp_f32_e32 v67, v67
	v_add_f32_e32 v52, 1.0, v52
	v_add_f32_e32 v53, 1.0, v53
	v_add_f32_e32 v54, 1.0, v54
	v_add_f32_e32 v55, 1.0, v55
	v_add_f32_e32 v56, 1.0, v56
	v_add_f32_e32 v57, 1.0, v57
	v_add_f32_e32 v58, 1.0, v58
	v_add_f32_e32 v59, 1.0, v59
	v_add_f32_e32 v60, 1.0, v60
	v_add_f32_e32 v61, 1.0, v61
	v_add_f32_e32 v62, 1.0, v62
	v_add_f32_e32 v63, 1.0, v63
	v_add_f32_e32 v64, 1.0, v64
	v_add_f32_e32 v65, 1.0, v65
	v_add_f32_e32 v66, 1.0, v66
	v_add_f32_e32 v67, 1.0, v67
	v_rcp_f32_e32 v52, v52
	v_rcp_f32_e32 v53, v53
	v_rcp_f32_e32 v54, v54
	v_rcp_f32_e32 v55, v55
	v_rcp_f32_e32 v56, v56
	v_rcp_f32_e32 v57, v57
	v_rcp_f32_e32 v58, v58
	v_rcp_f32_e32 v59, v59
	v_rcp_f32_e32 v60, v60
	v_rcp_f32_e32 v61, v61
	v_rcp_f32_e32 v62, v62
	v_rcp_f32_e32 v63, v63
	v_rcp_f32_e32 v64, v64
	v_rcp_f32_e32 v65, v65
	v_rcp_f32_e32 v66, v66
	v_rcp_f32_e32 v67, v67
	v_mul_f32_e32 v36, v36, v52
	v_mul_f32_e32 v37, v37, v53
	v_mul_f32_e32 v38, v38, v54
	v_mul_f32_e32 v39, v39, v55
	v_mul_f32_e32 v40, v40, v56
	v_mul_f32_e32 v41, v41, v57
	v_mul_f32_e32 v42, v42, v58
	v_mul_f32_e32 v43, v43, v59
	v_fma_f32 v44, v92, v60, v84
	v_fma_f32 v45, v93, v61, v85
	v_fma_f32 v46, v94, v62, v86
	v_fma_f32 v47, v95, v63, v87
	v_fma_f32 v48, v96, v64, v88
	v_fma_f32 v49, v97, v65, v89
	v_fma_f32 v50, v98, v66, v90
	v_fma_f32 v51, v99, v67, v91
	v_lshlrev_b32_e32 v68, 16, v32
	v_and_b32_e32 v69, 0xffff0000, v32
	v_lshlrev_b32_e32 v70, 16, v33
	v_and_b32_e32 v71, 0xffff0000, v33
	v_lshlrev_b32_e32 v72, 16, v34
	v_and_b32_e32 v73, 0xffff0000, v34
	v_lshlrev_b32_e32 v74, 16, v35
	v_and_b32_e32 v75, 0xffff0000, v35
	ds_write_b128 v82, v[44:47] offset:0
	ds_write_b128 v82, v[48:51] offset:16
	ds_write_b128 v82, v[36:39] offset:528
	ds_write_b128 v82, v[40:43] offset:544
	s_mov_b64 exec, s[48:49]
	ds_write_b128 v83, v[68:71] offset:0
	ds_write_b128 v83, v[72:75] offset:16
	s_mov_b64 exec, -1
	global_load_dwordx4 v[24:27], v[76:77], off
	global_load_dwordx4 v[28:31], v[78:79], off
	s_mov_b64 exec, s[48:49]
	global_load_dwordx4 v[32:35], v[80:81], off
	s_mov_b64 exec, -1
	v_lshl_add_u64 v[76:77], v[76:77], 0, s[46:47]
	v_lshl_add_u64 v[78:79], v[78:79], 0, s[46:47]
	v_lshl_add_u64 v[80:81], v[80:81], 0, s[46:47]
	s_waitcnt lgkmcnt(0)
	s_barrier
	s_waitcnt vmcnt(6)
	v_lshlrev_b32_e32 v36, 16, v0
	v_and_b32_e32 v37, 0xffff0000, v0
	v_lshlrev_b32_e32 v38, 16, v1
	v_and_b32_e32 v39, 0xffff0000, v1
	v_lshlrev_b32_e32 v40, 16, v2
	v_and_b32_e32 v41, 0xffff0000, v2
	v_lshlrev_b32_e32 v42, 16, v3
	v_and_b32_e32 v43, 0xffff0000, v3
	v_lshlrev_b32_e32 v44, 16, v4
	v_and_b32_e32 v45, 0xffff0000, v4
	v_lshlrev_b32_e32 v46, 16, v5
	v_and_b32_e32 v47, 0xffff0000, v5
	v_lshlrev_b32_e32 v48, 16, v6
	v_and_b32_e32 v49, 0xffff0000, v6
	v_lshlrev_b32_e32 v50, 16, v7
	v_and_b32_e32 v51, 0xffff0000, v7
	v_mul_f32_e32 v52, 0xbfb8aa3b, v36
	v_mul_f32_e32 v53, 0xbfb8aa3b, v37
	v_mul_f32_e32 v54, 0xbfb8aa3b, v38
	v_mul_f32_e32 v55, 0xbfb8aa3b, v39
	v_mul_f32_e32 v56, 0xbfb8aa3b, v40
	v_mul_f32_e32 v57, 0xbfb8aa3b, v41
	v_mul_f32_e32 v58, 0xbfb8aa3b, v42
	v_mul_f32_e32 v59, 0xbfb8aa3b, v43
	v_mul_f32_e32 v60, 0xbfb8aa3b, v44
	v_mul_f32_e32 v61, 0xbfb8aa3b, v45
	v_mul_f32_e32 v62, 0xbfb8aa3b, v46
	v_mul_f32_e32 v63, 0xbfb8aa3b, v47
	v_mul_f32_e32 v64, 0xbfb8aa3b, v48
	v_mul_f32_e32 v65, 0xbfb8aa3b, v49
	v_mul_f32_e32 v66, 0xbfb8aa3b, v50
	v_mul_f32_e32 v67, 0xbfb8aa3b, v51
	v_exp_f32_e32 v52, v52
	v_exp_f32_e32 v53, v53
	v_exp_f32_e32 v54, v54
	v_exp_f32_e32 v55, v55
	v_exp_f32_e32 v56, v56
	v_exp_f32_e32 v57, v57
	v_exp_f32_e32 v58, v58
	v_exp_f32_e32 v59, v59
	v_exp_f32_e32 v60, v60
	v_exp_f32_e32 v61, v61
	v_exp_f32_e32 v62, v62
	v_exp_f32_e32 v63, v63
	v_exp_f32_e32 v64, v64
	v_exp_f32_e32 v65, v65
	v_exp_f32_e32 v66, v66
	v_exp_f32_e32 v67, v67
	v_add_f32_e32 v52, 1.0, v52
	v_add_f32_e32 v53, 1.0, v53
	v_add_f32_e32 v54, 1.0, v54
	v_add_f32_e32 v55, 1.0, v55
	v_add_f32_e32 v56, 1.0, v56
	v_add_f32_e32 v57, 1.0, v57
	v_add_f32_e32 v58, 1.0, v58
	v_add_f32_e32 v59, 1.0, v59
	v_add_f32_e32 v60, 1.0, v60
	v_add_f32_e32 v61, 1.0, v61
	v_add_f32_e32 v62, 1.0, v62
	v_add_f32_e32 v63, 1.0, v63
	v_add_f32_e32 v64, 1.0, v64
	v_add_f32_e32 v65, 1.0, v65
	v_add_f32_e32 v66, 1.0, v66
	v_add_f32_e32 v67, 1.0, v67
	v_rcp_f32_e32 v52, v52
	v_rcp_f32_e32 v53, v53
	v_rcp_f32_e32 v54, v54
	v_rcp_f32_e32 v55, v55
	v_rcp_f32_e32 v56, v56
	v_rcp_f32_e32 v57, v57
	v_rcp_f32_e32 v58, v58
	v_rcp_f32_e32 v59, v59
	v_rcp_f32_e32 v60, v60
	v_rcp_f32_e32 v61, v61
	v_rcp_f32_e32 v62, v62
	v_rcp_f32_e32 v63, v63
	v_rcp_f32_e32 v64, v64
	v_rcp_f32_e32 v65, v65
	v_rcp_f32_e32 v66, v66
	v_rcp_f32_e32 v67, v67
	v_mul_f32_e32 v36, v36, v52
	v_mul_f32_e32 v37, v37, v53
	v_mul_f32_e32 v38, v38, v54
	v_mul_f32_e32 v39, v39, v55
	v_mul_f32_e32 v40, v40, v56
	v_mul_f32_e32 v41, v41, v57
	v_mul_f32_e32 v42, v42, v58
	v_mul_f32_e32 v43, v43, v59
	v_fma_f32 v44, v92, v60, v84
	v_fma_f32 v45, v93, v61, v85
	v_fma_f32 v46, v94, v62, v86
	v_fma_f32 v47, v95, v63, v87
	v_fma_f32 v48, v96, v64, v88
	v_fma_f32 v49, v97, v65, v89
	v_fma_f32 v50, v98, v66, v90
	v_fma_f32 v51, v99, v67, v91
	v_lshlrev_b32_e32 v68, 16, v8
	v_and_b32_e32 v69, 0xffff0000, v8
	v_lshlrev_b32_e32 v70, 16, v9
	v_and_b32_e32 v71, 0xffff0000, v9
	v_lshlrev_b32_e32 v72, 16, v10
	v_and_b32_e32 v73, 0xffff0000, v10
	v_lshlrev_b32_e32 v74, 16, v11
	v_and_b32_e32 v75, 0xffff0000, v11
	ds_write_b128 v82, v[44:47] offset:16896
	ds_write_b128 v82, v[48:51] offset:16912
	ds_write_b128 v82, v[36:39] offset:17424
	ds_write_b128 v82, v[40:43] offset:17440
	s_mov_b64 exec, s[48:49]
	ds_write_b128 v83, v[68:71] offset:2048
	ds_write_b128 v83, v[72:75] offset:2064
	s_mov_b64 exec, -1
	global_load_dwordx4 v[0:3], v[76:77], off
	global_load_dwordx4 v[4:7], v[78:79], off
	s_mov_b64 exec, s[48:49]
	global_load_dwordx4 v[8:11], v[80:81], off
	s_mov_b64 exec, -1
	v_lshl_add_u64 v[76:77], v[76:77], 0, s[46:47]
	v_lshl_add_u64 v[78:79], v[78:79], 0, s[46:47]
	v_lshl_add_u64 v[80:81], v[80:81], 0, s[46:47]
	s_waitcnt lgkmcnt(0)
	s_barrier
	s_waitcnt vmcnt(6)
	v_lshlrev_b32_e32 v36, 16, v12
	v_and_b32_e32 v37, 0xffff0000, v12
	v_lshlrev_b32_e32 v38, 16, v13
	v_and_b32_e32 v39, 0xffff0000, v13
	v_lshlrev_b32_e32 v40, 16, v14
	v_and_b32_e32 v41, 0xffff0000, v14
	v_lshlrev_b32_e32 v42, 16, v15
	v_and_b32_e32 v43, 0xffff0000, v15
	v_lshlrev_b32_e32 v44, 16, v16
	v_and_b32_e32 v45, 0xffff0000, v16
	v_lshlrev_b32_e32 v46, 16, v17
	v_and_b32_e32 v47, 0xffff0000, v17
	v_lshlrev_b32_e32 v48, 16, v18
	v_and_b32_e32 v49, 0xffff0000, v18
	v_lshlrev_b32_e32 v50, 16, v19
	v_and_b32_e32 v51, 0xffff0000, v19
	v_mul_f32_e32 v52, 0xbfb8aa3b, v36
	v_mul_f32_e32 v53, 0xbfb8aa3b, v37
	v_mul_f32_e32 v54, 0xbfb8aa3b, v38
	v_mul_f32_e32 v55, 0xbfb8aa3b, v39
	v_mul_f32_e32 v56, 0xbfb8aa3b, v40
	v_mul_f32_e32 v57, 0xbfb8aa3b, v41
	v_mul_f32_e32 v58, 0xbfb8aa3b, v42
	v_mul_f32_e32 v59, 0xbfb8aa3b, v43
	v_mul_f32_e32 v60, 0xbfb8aa3b, v44
	v_mul_f32_e32 v61, 0xbfb8aa3b, v45
	v_mul_f32_e32 v62, 0xbfb8aa3b, v46
	v_mul_f32_e32 v63, 0xbfb8aa3b, v47
	v_mul_f32_e32 v64, 0xbfb8aa3b, v48
	v_mul_f32_e32 v65, 0xbfb8aa3b, v49
	v_mul_f32_e32 v66, 0xbfb8aa3b, v50
	v_mul_f32_e32 v67, 0xbfb8aa3b, v51
	v_exp_f32_e32 v52, v52
	v_exp_f32_e32 v53, v53
	v_exp_f32_e32 v54, v54
	v_exp_f32_e32 v55, v55
	v_exp_f32_e32 v56, v56
	v_exp_f32_e32 v57, v57
	v_exp_f32_e32 v58, v58
	v_exp_f32_e32 v59, v59
	v_exp_f32_e32 v60, v60
	v_exp_f32_e32 v61, v61
	v_exp_f32_e32 v62, v62
	v_exp_f32_e32 v63, v63
	v_exp_f32_e32 v64, v64
	v_exp_f32_e32 v65, v65
	v_exp_f32_e32 v66, v66
	v_exp_f32_e32 v67, v67
	v_add_f32_e32 v52, 1.0, v52
	v_add_f32_e32 v53, 1.0, v53
	v_add_f32_e32 v54, 1.0, v54
	v_add_f32_e32 v55, 1.0, v55
	v_add_f32_e32 v56, 1.0, v56
	v_add_f32_e32 v57, 1.0, v57
	v_add_f32_e32 v58, 1.0, v58
	v_add_f32_e32 v59, 1.0, v59
	v_add_f32_e32 v60, 1.0, v60
	v_add_f32_e32 v61, 1.0, v61
	v_add_f32_e32 v62, 1.0, v62
	v_add_f32_e32 v63, 1.0, v63
	v_add_f32_e32 v64, 1.0, v64
	v_add_f32_e32 v65, 1.0, v65
	v_add_f32_e32 v66, 1.0, v66
	v_add_f32_e32 v67, 1.0, v67
	v_rcp_f32_e32 v52, v52
	v_rcp_f32_e32 v53, v53
	v_rcp_f32_e32 v54, v54
	v_rcp_f32_e32 v55, v55
	v_rcp_f32_e32 v56, v56
	v_rcp_f32_e32 v57, v57
	v_rcp_f32_e32 v58, v58
	v_rcp_f32_e32 v59, v59
	v_rcp_f32_e32 v60, v60
	v_rcp_f32_e32 v61, v61
	v_rcp_f32_e32 v62, v62
	v_rcp_f32_e32 v63, v63
	v_rcp_f32_e32 v64, v64
	v_rcp_f32_e32 v65, v65
	v_rcp_f32_e32 v66, v66
	v_rcp_f32_e32 v67, v67
	v_mul_f32_e32 v36, v36, v52
	v_mul_f32_e32 v37, v37, v53
	v_mul_f32_e32 v38, v38, v54
	v_mul_f32_e32 v39, v39, v55
	v_mul_f32_e32 v40, v40, v56
	v_mul_f32_e32 v41, v41, v57
	v_mul_f32_e32 v42, v42, v58
	v_mul_f32_e32 v43, v43, v59
	v_fma_f32 v44, v92, v60, v84
	v_fma_f32 v45, v93, v61, v85
	v_fma_f32 v46, v94, v62, v86
	v_fma_f32 v47, v95, v63, v87
	v_fma_f32 v48, v96, v64, v88
	v_fma_f32 v49, v97, v65, v89
	v_fma_f32 v50, v98, v66, v90
	v_fma_f32 v51, v99, v67, v91
	v_lshlrev_b32_e32 v68, 16, v20
	v_and_b32_e32 v69, 0xffff0000, v20
	v_lshlrev_b32_e32 v70, 16, v21
	v_and_b32_e32 v71, 0xffff0000, v21
	v_lshlrev_b32_e32 v72, 16, v22
	v_and_b32_e32 v73, 0xffff0000, v22
	v_lshlrev_b32_e32 v74, 16, v23
	v_and_b32_e32 v75, 0xffff0000, v23
	ds_write_b128 v82, v[44:47] offset:0
	ds_write_b128 v82, v[48:51] offset:16
	ds_write_b128 v82, v[36:39] offset:528
	ds_write_b128 v82, v[40:43] offset:544
	s_mov_b64 exec, s[48:49]
	ds_write_b128 v83, v[68:71] offset:0
	ds_write_b128 v83, v[72:75] offset:16
	s_mov_b64 exec, -1
	global_load_dwordx4 v[12:15], v[76:77], off
	global_load_dwordx4 v[16:19], v[78:79], off
	s_mov_b64 exec, s[48:49]
	global_load_dwordx4 v[20:23], v[80:81], off
	s_mov_b64 exec, -1
	v_lshl_add_u64 v[76:77], v[76:77], 0, s[46:47]
	v_lshl_add_u64 v[78:79], v[78:79], 0, s[46:47]
	v_lshl_add_u64 v[80:81], v[80:81], 0, s[46:47]
	s_waitcnt lgkmcnt(0)
	s_barrier
	s_waitcnt vmcnt(6)
	v_lshlrev_b32_e32 v36, 16, v24
	v_and_b32_e32 v37, 0xffff0000, v24
	v_lshlrev_b32_e32 v38, 16, v25
	v_and_b32_e32 v39, 0xffff0000, v25
	v_lshlrev_b32_e32 v40, 16, v26
	v_and_b32_e32 v41, 0xffff0000, v26
	v_lshlrev_b32_e32 v42, 16, v27
	v_and_b32_e32 v43, 0xffff0000, v27
	v_lshlrev_b32_e32 v44, 16, v28
	v_and_b32_e32 v45, 0xffff0000, v28
	v_lshlrev_b32_e32 v46, 16, v29
	v_and_b32_e32 v47, 0xffff0000, v29
	v_lshlrev_b32_e32 v48, 16, v30
	v_and_b32_e32 v49, 0xffff0000, v30
	v_lshlrev_b32_e32 v50, 16, v31
	v_and_b32_e32 v51, 0xffff0000, v31
	v_mul_f32_e32 v52, 0xbfb8aa3b, v36
	v_mul_f32_e32 v53, 0xbfb8aa3b, v37
	v_mul_f32_e32 v54, 0xbfb8aa3b, v38
	v_mul_f32_e32 v55, 0xbfb8aa3b, v39
	v_mul_f32_e32 v56, 0xbfb8aa3b, v40
	v_mul_f32_e32 v57, 0xbfb8aa3b, v41
	v_mul_f32_e32 v58, 0xbfb8aa3b, v42
	v_mul_f32_e32 v59, 0xbfb8aa3b, v43
	v_mul_f32_e32 v60, 0xbfb8aa3b, v44
	v_mul_f32_e32 v61, 0xbfb8aa3b, v45
	v_mul_f32_e32 v62, 0xbfb8aa3b, v46
	v_mul_f32_e32 v63, 0xbfb8aa3b, v47
	v_mul_f32_e32 v64, 0xbfb8aa3b, v48
	v_mul_f32_e32 v65, 0xbfb8aa3b, v49
	v_mul_f32_e32 v66, 0xbfb8aa3b, v50
	v_mul_f32_e32 v67, 0xbfb8aa3b, v51
	v_exp_f32_e32 v52, v52
	v_exp_f32_e32 v53, v53
	v_exp_f32_e32 v54, v54
	v_exp_f32_e32 v55, v55
	v_exp_f32_e32 v56, v56
	v_exp_f32_e32 v57, v57
	v_exp_f32_e32 v58, v58
	v_exp_f32_e32 v59, v59
	v_exp_f32_e32 v60, v60
	v_exp_f32_e32 v61, v61
	v_exp_f32_e32 v62, v62
	v_exp_f32_e32 v63, v63
	v_exp_f32_e32 v64, v64
	v_exp_f32_e32 v65, v65
	v_exp_f32_e32 v66, v66
	v_exp_f32_e32 v67, v67
	v_add_f32_e32 v52, 1.0, v52
	v_add_f32_e32 v53, 1.0, v53
	v_add_f32_e32 v54, 1.0, v54
	v_add_f32_e32 v55, 1.0, v55
	v_add_f32_e32 v56, 1.0, v56
	v_add_f32_e32 v57, 1.0, v57
	v_add_f32_e32 v58, 1.0, v58
	v_add_f32_e32 v59, 1.0, v59
	v_add_f32_e32 v60, 1.0, v60
	v_add_f32_e32 v61, 1.0, v61
	v_add_f32_e32 v62, 1.0, v62
	v_add_f32_e32 v63, 1.0, v63
	v_add_f32_e32 v64, 1.0, v64
	v_add_f32_e32 v65, 1.0, v65
	v_add_f32_e32 v66, 1.0, v66
	v_add_f32_e32 v67, 1.0, v67
	v_rcp_f32_e32 v52, v52
	v_rcp_f32_e32 v53, v53
	v_rcp_f32_e32 v54, v54
	v_rcp_f32_e32 v55, v55
	v_rcp_f32_e32 v56, v56
	v_rcp_f32_e32 v57, v57
	v_rcp_f32_e32 v58, v58
	v_rcp_f32_e32 v59, v59
	v_rcp_f32_e32 v60, v60
	v_rcp_f32_e32 v61, v61
	v_rcp_f32_e32 v62, v62
	v_rcp_f32_e32 v63, v63
	v_rcp_f32_e32 v64, v64
	v_rcp_f32_e32 v65, v65
	v_rcp_f32_e32 v66, v66
	v_rcp_f32_e32 v67, v67
	v_mul_f32_e32 v36, v36, v52
	v_mul_f32_e32 v37, v37, v53
	v_mul_f32_e32 v38, v38, v54
	v_mul_f32_e32 v39, v39, v55
	v_mul_f32_e32 v40, v40, v56
	v_mul_f32_e32 v41, v41, v57
	v_mul_f32_e32 v42, v42, v58
	v_mul_f32_e32 v43, v43, v59
	v_fma_f32 v44, v92, v60, v84
	v_fma_f32 v45, v93, v61, v85
	v_fma_f32 v46, v94, v62, v86
	v_fma_f32 v47, v95, v63, v87
	v_fma_f32 v48, v96, v64, v88
	v_fma_f32 v49, v97, v65, v89
	v_fma_f32 v50, v98, v66, v90
	v_fma_f32 v51, v99, v67, v91
	v_lshlrev_b32_e32 v68, 16, v32
	v_and_b32_e32 v69, 0xffff0000, v32
	v_lshlrev_b32_e32 v70, 16, v33
	v_and_b32_e32 v71, 0xffff0000, v33
	v_lshlrev_b32_e32 v72, 16, v34
	v_and_b32_e32 v73, 0xffff0000, v34
	v_lshlrev_b32_e32 v74, 16, v35
	v_and_b32_e32 v75, 0xffff0000, v35
	ds_write_b128 v82, v[44:47] offset:16896
	ds_write_b128 v82, v[48:51] offset:16912
	ds_write_b128 v82, v[36:39] offset:17424
	ds_write_b128 v82, v[40:43] offset:17440
	s_mov_b64 exec, s[48:49]
	ds_write_b128 v83, v[68:71] offset:2048
	ds_write_b128 v83, v[72:75] offset:2064
	s_mov_b64 exec, -1
	global_load_dwordx4 v[24:27], v[76:77], off
	global_load_dwordx4 v[28:31], v[78:79], off
	s_mov_b64 exec, s[48:49]
	global_load_dwordx4 v[32:35], v[80:81], off
	s_mov_b64 exec, -1
	v_lshl_add_u64 v[76:77], v[76:77], 0, s[46:47]
	v_lshl_add_u64 v[78:79], v[78:79], 0, s[46:47]
	v_lshl_add_u64 v[80:81], v[80:81], 0, s[46:47]
	s_waitcnt lgkmcnt(0)
	s_barrier
	s_waitcnt vmcnt(6)
	v_lshlrev_b32_e32 v36, 16, v0
	v_and_b32_e32 v37, 0xffff0000, v0
	v_lshlrev_b32_e32 v38, 16, v1
	v_and_b32_e32 v39, 0xffff0000, v1
	v_lshlrev_b32_e32 v40, 16, v2
	v_and_b32_e32 v41, 0xffff0000, v2
	v_lshlrev_b32_e32 v42, 16, v3
	v_and_b32_e32 v43, 0xffff0000, v3
	v_lshlrev_b32_e32 v44, 16, v4
	v_and_b32_e32 v45, 0xffff0000, v4
	v_lshlrev_b32_e32 v46, 16, v5
	v_and_b32_e32 v47, 0xffff0000, v5
	v_lshlrev_b32_e32 v48, 16, v6
	v_and_b32_e32 v49, 0xffff0000, v6
	v_lshlrev_b32_e32 v50, 16, v7
	v_and_b32_e32 v51, 0xffff0000, v7
	v_mul_f32_e32 v52, 0xbfb8aa3b, v36
	v_mul_f32_e32 v53, 0xbfb8aa3b, v37
	v_mul_f32_e32 v54, 0xbfb8aa3b, v38
	v_mul_f32_e32 v55, 0xbfb8aa3b, v39
	v_mul_f32_e32 v56, 0xbfb8aa3b, v40
	v_mul_f32_e32 v57, 0xbfb8aa3b, v41
	v_mul_f32_e32 v58, 0xbfb8aa3b, v42
	v_mul_f32_e32 v59, 0xbfb8aa3b, v43
	v_mul_f32_e32 v60, 0xbfb8aa3b, v44
	v_mul_f32_e32 v61, 0xbfb8aa3b, v45
	v_mul_f32_e32 v62, 0xbfb8aa3b, v46
	v_mul_f32_e32 v63, 0xbfb8aa3b, v47
	v_mul_f32_e32 v64, 0xbfb8aa3b, v48
	v_mul_f32_e32 v65, 0xbfb8aa3b, v49
	v_mul_f32_e32 v66, 0xbfb8aa3b, v50
	v_mul_f32_e32 v67, 0xbfb8aa3b, v51
	v_exp_f32_e32 v52, v52
	v_exp_f32_e32 v53, v53
	v_exp_f32_e32 v54, v54
	v_exp_f32_e32 v55, v55
	v_exp_f32_e32 v56, v56
	v_exp_f32_e32 v57, v57
	v_exp_f32_e32 v58, v58
	v_exp_f32_e32 v59, v59
	v_exp_f32_e32 v60, v60
	v_exp_f32_e32 v61, v61
	v_exp_f32_e32 v62, v62
	v_exp_f32_e32 v63, v63
	v_exp_f32_e32 v64, v64
	v_exp_f32_e32 v65, v65
	v_exp_f32_e32 v66, v66
	v_exp_f32_e32 v67, v67
	v_add_f32_e32 v52, 1.0, v52
	v_add_f32_e32 v53, 1.0, v53
	v_add_f32_e32 v54, 1.0, v54
	v_add_f32_e32 v55, 1.0, v55
	v_add_f32_e32 v56, 1.0, v56
	v_add_f32_e32 v57, 1.0, v57
	v_add_f32_e32 v58, 1.0, v58
	v_add_f32_e32 v59, 1.0, v59
	v_add_f32_e32 v60, 1.0, v60
	v_add_f32_e32 v61, 1.0, v61
	v_add_f32_e32 v62, 1.0, v62
	v_add_f32_e32 v63, 1.0, v63
	v_add_f32_e32 v64, 1.0, v64
	v_add_f32_e32 v65, 1.0, v65
	v_add_f32_e32 v66, 1.0, v66
	v_add_f32_e32 v67, 1.0, v67
	v_rcp_f32_e32 v52, v52
	v_rcp_f32_e32 v53, v53
	v_rcp_f32_e32 v54, v54
	v_rcp_f32_e32 v55, v55
	v_rcp_f32_e32 v56, v56
	v_rcp_f32_e32 v57, v57
	v_rcp_f32_e32 v58, v58
	v_rcp_f32_e32 v59, v59
	v_rcp_f32_e32 v60, v60
	v_rcp_f32_e32 v61, v61
	v_rcp_f32_e32 v62, v62
	v_rcp_f32_e32 v63, v63
	v_rcp_f32_e32 v64, v64
	v_rcp_f32_e32 v65, v65
	v_rcp_f32_e32 v66, v66
	v_rcp_f32_e32 v67, v67
	v_mul_f32_e32 v36, v36, v52
	v_mul_f32_e32 v37, v37, v53
	v_mul_f32_e32 v38, v38, v54
	v_mul_f32_e32 v39, v39, v55
	v_mul_f32_e32 v40, v40, v56
	v_mul_f32_e32 v41, v41, v57
	v_mul_f32_e32 v42, v42, v58
	v_mul_f32_e32 v43, v43, v59
	v_fma_f32 v44, v92, v60, v84
	v_fma_f32 v45, v93, v61, v85
	v_fma_f32 v46, v94, v62, v86
	v_fma_f32 v47, v95, v63, v87
	v_fma_f32 v48, v96, v64, v88
	v_fma_f32 v49, v97, v65, v89
	v_fma_f32 v50, v98, v66, v90
	v_fma_f32 v51, v99, v67, v91
	v_lshlrev_b32_e32 v68, 16, v8
	v_and_b32_e32 v69, 0xffff0000, v8
	v_lshlrev_b32_e32 v70, 16, v9
	v_and_b32_e32 v71, 0xffff0000, v9
	v_lshlrev_b32_e32 v72, 16, v10
	v_and_b32_e32 v73, 0xffff0000, v10
	v_lshlrev_b32_e32 v74, 16, v11
	v_and_b32_e32 v75, 0xffff0000, v11
	ds_write_b128 v82, v[44:47] offset:0
	ds_write_b128 v82, v[48:51] offset:16
	ds_write_b128 v82, v[36:39] offset:528
	ds_write_b128 v82, v[40:43] offset:544
	s_mov_b64 exec, s[48:49]
	ds_write_b128 v83, v[68:71] offset:0
	ds_write_b128 v83, v[72:75] offset:16
	s_mov_b64 exec, -1
	global_load_dwordx4 v[0:3], v[76:77], off
	global_load_dwordx4 v[4:7], v[78:79], off
	s_mov_b64 exec, s[48:49]
	global_load_dwordx4 v[8:11], v[80:81], off
	s_mov_b64 exec, -1
	v_lshl_add_u64 v[76:77], v[76:77], 0, s[46:47]
	v_lshl_add_u64 v[78:79], v[78:79], 0, s[46:47]
	v_lshl_add_u64 v[80:81], v[80:81], 0, s[46:47]
	s_waitcnt lgkmcnt(0)
	s_barrier
	s_add_i32 s50, s50, 1
	s_cmp_lt_u32 s50, 42
	s_cbranch_scc1 .Lhs_loop
	s_waitcnt vmcnt(6)
	v_lshlrev_b32_e32 v36, 16, v12
	v_and_b32_e32 v37, 0xffff0000, v12
	v_lshlrev_b32_e32 v38, 16, v13
	v_and_b32_e32 v39, 0xffff0000, v13
	v_lshlrev_b32_e32 v40, 16, v14
	v_and_b32_e32 v41, 0xffff0000, v14
	v_lshlrev_b32_e32 v42, 16, v15
	v_and_b32_e32 v43, 0xffff0000, v15
	v_lshlrev_b32_e32 v44, 16, v16
	v_and_b32_e32 v45, 0xffff0000, v16
	v_lshlrev_b32_e32 v46, 16, v17
	v_and_b32_e32 v47, 0xffff0000, v17
	v_lshlrev_b32_e32 v48, 16, v18
	v_and_b32_e32 v49, 0xffff0000, v18
	v_lshlrev_b32_e32 v50, 16, v19
	v_and_b32_e32 v51, 0xffff0000, v19
	v_mul_f32_e32 v52, 0xbfb8aa3b, v36
	v_mul_f32_e32 v53, 0xbfb8aa3b, v37
	v_mul_f32_e32 v54, 0xbfb8aa3b, v38
	v_mul_f32_e32 v55, 0xbfb8aa3b, v39
	v_mul_f32_e32 v56, 0xbfb8aa3b, v40
	v_mul_f32_e32 v57, 0xbfb8aa3b, v41
	v_mul_f32_e32 v58, 0xbfb8aa3b, v42
	v_mul_f32_e32 v59, 0xbfb8aa3b, v43
	v_mul_f32_e32 v60, 0xbfb8aa3b, v44
	v_mul_f32_e32 v61, 0xbfb8aa3b, v45
	v_mul_f32_e32 v62, 0xbfb8aa3b, v46
	v_mul_f32_e32 v63, 0xbfb8aa3b, v47
	v_mul_f32_e32 v64, 0xbfb8aa3b, v48
	v_mul_f32_e32 v65, 0xbfb8aa3b, v49
	v_mul_f32_e32 v66, 0xbfb8aa3b, v50
	v_mul_f32_e32 v67, 0xbfb8aa3b, v51
	v_exp_f32_e32 v52, v52
	v_exp_f32_e32 v53, v53
	v_exp_f32_e32 v54, v54
	v_exp_f32_e32 v55, v55
	v_exp_f32_e32 v56, v56
	v_exp_f32_e32 v57, v57
	v_exp_f32_e32 v58, v58
	v_exp_f32_e32 v59, v59
	v_exp_f32_e32 v60, v60
	v_exp_f32_e32 v61, v61
	v_exp_f32_e32 v62, v62
	v_exp_f32_e32 v63, v63
	v_exp_f32_e32 v64, v64
	v_exp_f32_e32 v65, v65
	v_exp_f32_e32 v66, v66
	v_exp_f32_e32 v67, v67
	v_add_f32_e32 v52, 1.0, v52
	v_add_f32_e32 v53, 1.0, v53
	v_add_f32_e32 v54, 1.0, v54
	v_add_f32_e32 v55, 1.0, v55
	v_add_f32_e32 v56, 1.0, v56
	v_add_f32_e32 v57, 1.0, v57
	v_add_f32_e32 v58, 1.0, v58
	v_add_f32_e32 v59, 1.0, v59
	v_add_f32_e32 v60, 1.0, v60
	v_add_f32_e32 v61, 1.0, v61
	v_add_f32_e32 v62, 1.0, v62
	v_add_f32_e32 v63, 1.0, v63
	v_add_f32_e32 v64, 1.0, v64
	v_add_f32_e32 v65, 1.0, v65
	v_add_f32_e32 v66, 1.0, v66
	v_add_f32_e32 v67, 1.0, v67
	v_rcp_f32_e32 v52, v52
	v_rcp_f32_e32 v53, v53
	v_rcp_f32_e32 v54, v54
	v_rcp_f32_e32 v55, v55
	v_rcp_f32_e32 v56, v56
	v_rcp_f32_e32 v57, v57
	v_rcp_f32_e32 v58, v58
	v_rcp_f32_e32 v59, v59
	v_rcp_f32_e32 v60, v60
	v_rcp_f32_e32 v61, v61
	v_rcp_f32_e32 v62, v62
	v_rcp_f32_e32 v63, v63
	v_rcp_f32_e32 v64, v64
	v_rcp_f32_e32 v65, v65
	v_rcp_f32_e32 v66, v66
	v_rcp_f32_e32 v67, v67
	v_mul_f32_e32 v36, v36, v52
	v_mul_f32_e32 v37, v37, v53
	v_mul_f32_e32 v38, v38, v54
	v_mul_f32_e32 v39, v39, v55
	v_mul_f32_e32 v40, v40, v56
	v_mul_f32_e32 v41, v41, v57
	v_mul_f32_e32 v42, v42, v58
	v_mul_f32_e32 v43, v43, v59
	v_fma_f32 v44, v92, v60, v84
	v_fma_f32 v45, v93, v61, v85
	v_fma_f32 v46, v94, v62, v86
	v_fma_f32 v47, v95, v63, v87
	v_fma_f32 v48, v96, v64, v88
	v_fma_f32 v49, v97, v65, v89
	v_fma_f32 v50, v98, v66, v90
	v_fma_f32 v51, v99, v67, v91
	v_lshlrev_b32_e32 v68, 16, v20
	v_and_b32_e32 v69, 0xffff0000, v20
	v_lshlrev_b32_e32 v70, 16, v21
	v_and_b32_e32 v71, 0xffff0000, v21
	v_lshlrev_b32_e32 v72, 16, v22
	v_and_b32_e32 v73, 0xffff0000, v22
	v_lshlrev_b32_e32 v74, 16, v23
	v_and_b32_e32 v75, 0xffff0000, v23
	ds_write_b128 v82, v[44:47] offset:16896
	ds_write_b128 v82, v[48:51] offset:16912
	ds_write_b128 v82, v[36:39] offset:17424
	ds_write_b128 v82, v[40:43] offset:17440
	s_mov_b64 exec, s[48:49]
	ds_write_b128 v83, v[68:71] offset:2048
	ds_write_b128 v83, v[72:75] offset:2064
	s_mov_b64 exec, -1
	global_load_dwordx4 v[12:15], v[76:77], off
	global_load_dwordx4 v[16:19], v[78:79], off
	s_mov_b64 exec, s[48:49]
	global_load_dwordx4 v[20:23], v[80:81], off
	s_mov_b64 exec, -1
	v_lshl_add_u64 v[76:77], v[76:77], 0, s[46:47]
	v_lshl_add_u64 v[78:79], v[78:79], 0, s[46:47]
	v_lshl_add_u64 v[80:81], v[80:81], 0, s[46:47]
	s_waitcnt lgkmcnt(0)
	s_barrier
	s_waitcnt vmcnt(6)
	v_lshlrev_b32_e32 v36, 16, v24
	v_and_b32_e32 v37, 0xffff0000, v24
	v_lshlrev_b32_e32 v38, 16, v25
	v_and_b32_e32 v39, 0xffff0000, v25
	v_lshlrev_b32_e32 v40, 16, v26
	v_and_b32_e32 v41, 0xffff0000, v26
	v_lshlrev_b32_e32 v42, 16, v27
	v_and_b32_e32 v43, 0xffff0000, v27
	v_lshlrev_b32_e32 v44, 16, v28
	v_and_b32_e32 v45, 0xffff0000, v28
	v_lshlrev_b32_e32 v46, 16, v29
	v_and_b32_e32 v47, 0xffff0000, v29
	v_lshlrev_b32_e32 v48, 16, v30
	v_and_b32_e32 v49, 0xffff0000, v30
	v_lshlrev_b32_e32 v50, 16, v31
	v_and_b32_e32 v51, 0xffff0000, v31
	v_mul_f32_e32 v52, 0xbfb8aa3b, v36
	v_mul_f32_e32 v53, 0xbfb8aa3b, v37
	v_mul_f32_e32 v54, 0xbfb8aa3b, v38
	v_mul_f32_e32 v55, 0xbfb8aa3b, v39
	v_mul_f32_e32 v56, 0xbfb8aa3b, v40
	v_mul_f32_e32 v57, 0xbfb8aa3b, v41
	v_mul_f32_e32 v58, 0xbfb8aa3b, v42
	v_mul_f32_e32 v59, 0xbfb8aa3b, v43
	v_mul_f32_e32 v60, 0xbfb8aa3b, v44
	v_mul_f32_e32 v61, 0xbfb8aa3b, v45
	v_mul_f32_e32 v62, 0xbfb8aa3b, v46
	v_mul_f32_e32 v63, 0xbfb8aa3b, v47
	v_mul_f32_e32 v64, 0xbfb8aa3b, v48
	v_mul_f32_e32 v65, 0xbfb8aa3b, v49
	v_mul_f32_e32 v66, 0xbfb8aa3b, v50
	v_mul_f32_e32 v67, 0xbfb8aa3b, v51
	v_exp_f32_e32 v52, v52
	v_exp_f32_e32 v53, v53
	v_exp_f32_e32 v54, v54
	v_exp_f32_e32 v55, v55
	v_exp_f32_e32 v56, v56
	v_exp_f32_e32 v57, v57
	v_exp_f32_e32 v58, v58
	v_exp_f32_e32 v59, v59
	v_exp_f32_e32 v60, v60
	v_exp_f32_e32 v61, v61
	v_exp_f32_e32 v62, v62
	v_exp_f32_e32 v63, v63
	v_exp_f32_e32 v64, v64
	v_exp_f32_e32 v65, v65
	v_exp_f32_e32 v66, v66
	v_exp_f32_e32 v67, v67
	v_add_f32_e32 v52, 1.0, v52
	v_add_f32_e32 v53, 1.0, v53
	v_add_f32_e32 v54, 1.0, v54
	v_add_f32_e32 v55, 1.0, v55
	v_add_f32_e32 v56, 1.0, v56
	v_add_f32_e32 v57, 1.0, v57
	v_add_f32_e32 v58, 1.0, v58
	v_add_f32_e32 v59, 1.0, v59
	v_add_f32_e32 v60, 1.0, v60
	v_add_f32_e32 v61, 1.0, v61
	v_add_f32_e32 v62, 1.0, v62
	v_add_f32_e32 v63, 1.0, v63
	v_add_f32_e32 v64, 1.0, v64
	v_add_f32_e32 v65, 1.0, v65
	v_add_f32_e32 v66, 1.0, v66
	v_add_f32_e32 v67, 1.0, v67
	v_rcp_f32_e32 v52, v52
	v_rcp_f32_e32 v53, v53
	v_rcp_f32_e32 v54, v54
	v_rcp_f32_e32 v55, v55
	v_rcp_f32_e32 v56, v56
	v_rcp_f32_e32 v57, v57
	v_rcp_f32_e32 v58, v58
	v_rcp_f32_e32 v59, v59
	v_rcp_f32_e32 v60, v60
	v_rcp_f32_e32 v61, v61
	v_rcp_f32_e32 v62, v62
	v_rcp_f32_e32 v63, v63
	v_rcp_f32_e32 v64, v64
	v_rcp_f32_e32 v65, v65
	v_rcp_f32_e32 v66, v66
	v_rcp_f32_e32 v67, v67
	v_mul_f32_e32 v36, v36, v52
	v_mul_f32_e32 v37, v37, v53
	v_mul_f32_e32 v38, v38, v54
	v_mul_f32_e32 v39, v39, v55
	v_mul_f32_e32 v40, v40, v56
	v_mul_f32_e32 v41, v41, v57
	v_mul_f32_e32 v42, v42, v58
	v_mul_f32_e32 v43, v43, v59
	v_fma_f32 v44, v92, v60, v84
	v_fma_f32 v45, v93, v61, v85
	v_fma_f32 v46, v94, v62, v86
	v_fma_f32 v47, v95, v63, v87
	v_fma_f32 v48, v96, v64, v88
	v_fma_f32 v49, v97, v65, v89
	v_fma_f32 v50, v98, v66, v90
	v_fma_f32 v51, v99, v67, v91
	v_lshlrev_b32_e32 v68, 16, v32
	v_and_b32_e32 v69, 0xffff0000, v32
	v_lshlrev_b32_e32 v70, 16, v33
	v_and_b32_e32 v71, 0xffff0000, v33
	v_lshlrev_b32_e32 v72, 16, v34
	v_and_b32_e32 v73, 0xffff0000, v34
	v_lshlrev_b32_e32 v74, 16, v35
	v_and_b32_e32 v75, 0xffff0000, v35
	ds_write_b128 v82, v[44:47] offset:0
	ds_write_b128 v82, v[48:51] offset:16
	ds_write_b128 v82, v[36:39] offset:528
	ds_write_b128 v82, v[40:43] offset:544
	s_mov_b64 exec, s[48:49]
	ds_write_b128 v83, v[68:71] offset:0
	ds_write_b128 v83, v[72:75] offset:16
	s_mov_b64 exec, -1
	global_load_dwordx4 v[24:27], v[76:77], off
	global_load_dwordx4 v[28:31], v[78:79], off
	s_mov_b64 exec, s[48:49]
	global_load_dwordx4 v[32:35], v[80:81], off
	s_mov_b64 exec, -1
	v_lshl_add_u64 v[76:77], v[76:77], 0, s[46:47]
	v_lshl_add_u64 v[78:79], v[78:79], 0, s[46:47]
	v_lshl_add_u64 v[80:81], v[80:81], 0, s[46:47]
	s_waitcnt lgkmcnt(0)
	s_barrier
	s_waitcnt vmcnt(6)
	v_lshlrev_b32_e32 v36, 16, v0
	v_and_b32_e32 v37, 0xffff0000, v0
	v_lshlrev_b32_e32 v38, 16, v1
	v_and_b32_e32 v39, 0xffff0000, v1
	v_lshlrev_b32_e32 v40, 16, v2
	v_and_b32_e32 v41, 0xffff0000, v2
	v_lshlrev_b32_e32 v42, 16, v3
	v_and_b32_e32 v43, 0xffff0000, v3
	v_lshlrev_b32_e32 v44, 16, v4
	v_and_b32_e32 v45, 0xffff0000, v4
	v_lshlrev_b32_e32 v46, 16, v5
	v_and_b32_e32 v47, 0xffff0000, v5
	v_lshlrev_b32_e32 v48, 16, v6
	v_and_b32_e32 v49, 0xffff0000, v6
	v_lshlrev_b32_e32 v50, 16, v7
	v_and_b32_e32 v51, 0xffff0000, v7
	v_mul_f32_e32 v52, 0xbfb8aa3b, v36
	v_mul_f32_e32 v53, 0xbfb8aa3b, v37
	v_mul_f32_e32 v54, 0xbfb8aa3b, v38
	v_mul_f32_e32 v55, 0xbfb8aa3b, v39
	v_mul_f32_e32 v56, 0xbfb8aa3b, v40
	v_mul_f32_e32 v57, 0xbfb8aa3b, v41
	v_mul_f32_e32 v58, 0xbfb8aa3b, v42
	v_mul_f32_e32 v59, 0xbfb8aa3b, v43
	v_mul_f32_e32 v60, 0xbfb8aa3b, v44
	v_mul_f32_e32 v61, 0xbfb8aa3b, v45
	v_mul_f32_e32 v62, 0xbfb8aa3b, v46
	v_mul_f32_e32 v63, 0xbfb8aa3b, v47
	v_mul_f32_e32 v64, 0xbfb8aa3b, v48
	v_mul_f32_e32 v65, 0xbfb8aa3b, v49
	v_mul_f32_e32 v66, 0xbfb8aa3b, v50
	v_mul_f32_e32 v67, 0xbfb8aa3b, v51
	v_exp_f32_e32 v52, v52
	v_exp_f32_e32 v53, v53
	v_exp_f32_e32 v54, v54
	v_exp_f32_e32 v55, v55
	v_exp_f32_e32 v56, v56
	v_exp_f32_e32 v57, v57
	v_exp_f32_e32 v58, v58
	v_exp_f32_e32 v59, v59
	v_exp_f32_e32 v60, v60
	v_exp_f32_e32 v61, v61
	v_exp_f32_e32 v62, v62
	v_exp_f32_e32 v63, v63
	v_exp_f32_e32 v64, v64
	v_exp_f32_e32 v65, v65
	v_exp_f32_e32 v66, v66
	v_exp_f32_e32 v67, v67
	v_add_f32_e32 v52, 1.0, v52
	v_add_f32_e32 v53, 1.0, v53
	v_add_f32_e32 v54, 1.0, v54
	v_add_f32_e32 v55, 1.0, v55
	v_add_f32_e32 v56, 1.0, v56
	v_add_f32_e32 v57, 1.0, v57
	v_add_f32_e32 v58, 1.0, v58
	v_add_f32_e32 v59, 1.0, v59
	v_add_f32_e32 v60, 1.0, v60
	v_add_f32_e32 v61, 1.0, v61
	v_add_f32_e32 v62, 1.0, v62
	v_add_f32_e32 v63, 1.0, v63
	v_add_f32_e32 v64, 1.0, v64
	v_add_f32_e32 v65, 1.0, v65
	v_add_f32_e32 v66, 1.0, v66
	v_add_f32_e32 v67, 1.0, v67
	v_rcp_f32_e32 v52, v52
	v_rcp_f32_e32 v53, v53
	v_rcp_f32_e32 v54, v54
	v_rcp_f32_e32 v55, v55
	v_rcp_f32_e32 v56, v56
	v_rcp_f32_e32 v57, v57
	v_rcp_f32_e32 v58, v58
	v_rcp_f32_e32 v59, v59
	v_rcp_f32_e32 v60, v60
	v_rcp_f32_e32 v61, v61
	v_rcp_f32_e32 v62, v62
	v_rcp_f32_e32 v63, v63
	v_rcp_f32_e32 v64, v64
	v_rcp_f32_e32 v65, v65
	v_rcp_f32_e32 v66, v66
	v_rcp_f32_e32 v67, v67
	v_mul_f32_e32 v36, v36, v52
	v_mul_f32_e32 v37, v37, v53
	v_mul_f32_e32 v38, v38, v54
	v_mul_f32_e32 v39, v39, v55
	v_mul_f32_e32 v40, v40, v56
	v_mul_f32_e32 v41, v41, v57
	v_mul_f32_e32 v42, v42, v58
	v_mul_f32_e32 v43, v43, v59
	v_fma_f32 v44, v92, v60, v84
	v_fma_f32 v45, v93, v61, v85
	v_fma_f32 v46, v94, v62, v86
	v_fma_f32 v47, v95, v63, v87
	v_fma_f32 v48, v96, v64, v88
	v_fma_f32 v49, v97, v65, v89
	v_fma_f32 v50, v98, v66, v90
	v_fma_f32 v51, v99, v67, v91
	v_lshlrev_b32_e32 v68, 16, v8
	v_and_b32_e32 v69, 0xffff0000, v8
	v_lshlrev_b32_e32 v70, 16, v9
	v_and_b32_e32 v71, 0xffff0000, v9
	v_lshlrev_b32_e32 v72, 16, v10
	v_and_b32_e32 v73, 0xffff0000, v10
	v_lshlrev_b32_e32 v74, 16, v11
	v_and_b32_e32 v75, 0xffff0000, v11
	ds_write_b128 v82, v[44:47] offset:16896
	ds_write_b128 v82, v[48:51] offset:16912
	ds_write_b128 v82, v[36:39] offset:17424
	ds_write_b128 v82, v[40:43] offset:17440
	s_mov_b64 exec, s[48:49]
	ds_write_b128 v83, v[68:71] offset:2048
	ds_write_b128 v83, v[72:75] offset:2064
	s_mov_b64 exec, -1
	global_load_dwordx4 v[0:3], v[76:77], off
	global_load_dwordx4 v[4:7], v[78:79], off
	s_mov_b64 exec, s[48:49]
	global_load_dwordx4 v[8:11], v[80:81], off
	s_mov_b64 exec, -1
	v_lshl_add_u64 v[76:77], v[76:77], 0, s[46:47]
	v_lshl_add_u64 v[78:79], v[78:79], 0, s[46:47]
	v_lshl_add_u64 v[80:81], v[80:81], 0, s[46:47]
	s_waitcnt lgkmcnt(0)
	s_barrier
	s_waitcnt vmcnt(0)
	s_barrier

.LBB0_1192:
	s_or_b64 exec, exec, s[0:1]
	s_waitcnt vmcnt(0)
	v_lshlrev_b32_e32 v94, 16, v91
	v_pk_add_f32 v[92:93], v[92:93], v[94:95] op_sel_hi:[1,0] neg_lo:[0,1] neg_hi:[0,1]
	s_mov_b32 s6, 0
	v_pk_mul_f32 v[88:89], v[88:89], v[92:93]
	v_mov_b32_e32 v95, v90
	v_add_f32_e32 v88, v88, v94
	v_add_f32_e32 v88, v88, v89
	v_mul_f32_e32 v88, 0xbfb8aa3b, v88
	v_exp_f32_e32 v88, v88
	v_mov_b32_e32 v112, v90
	v_mov_b32_e32 v113, v90
	v_mov_b32_e32 v114, v90
	v_add_f32_e32 v88, 1.0, v88
	v_div_scale_f32 v89, s[0:1], v88, v88, 1.0
	v_rcp_f32_e32 v91, v89
	v_div_scale_f32 v92, vcc, 1.0, v88, 1.0
	s_mov_b64 s[0:1], 0
	v_fma_f32 v93, -v89, v91, 1.0
	v_fmac_f32_e32 v91, v93, v91
	v_mul_f32_e32 v93, v92, v91
	v_fma_f32 v94, -v89, v93, v92
	v_fmac_f32_e32 v93, v94, v91
	v_fma_f32 v89, -v89, v93, v92
	v_div_fmas_f32 v89, v89, v91, v93
	v_div_fixup_f32 v88, v89, v88, 1.0
	ds_write_b32 v124, v88
	v_mov_b32_e32 v91, v90
	v_mov_b32_e32 v88, v90
	v_mov_b32_e32 v89, v90
	v_mov_b32_e32 v92, v90
	v_mov_b32_e32 v93, v90
	v_mov_b32_e32 v94, v90
	v_mov_b32_e32 v115, v90
	v_mov_b32_e32 v116, v90
	v_mov_b32_e32 v117, v90
	v_mov_b32_e32 v118, v90
	v_mov_b32_e32 v119, v90
	s_waitcnt lgkmcnt(0)
	s_barrier
	v_readlane_b32 s0, v255, 33
	v_readlane_b32 s1, v255, 34
	v_and_b32_e32 v151, 63, v164
	v_lshrrev_b32_e32 v152, 6, v164
	v_lshlrev_b32_e32 v148, 2, v151
	v_lshrrev_b32_e32 v153, 4, v151
	v_and_b32_e32 v154, 15, v151
	v_lshlrev_b32_e32 v149, 11, v153
	v_lshl_add_u32 v149, v152, 8, v149
	v_lshl_add_u32 v149, v154, 4, v149
	v_lshlrev_b32_e32 v150, 13, v153
	v_lshl_add_u32 v150, v152, 8, v150
	v_lshl_add_u32 v150, v154, 4, v150
	v_add_u32_e32 v150, 0x2000, v150
	global_load_dwordx4 v[136:139], v149, s[0:1]
	v_add_u32_e32 v149, 0x2000, v149
	ds_read_b32 v132, v148 offset:0
	global_load_dwordx4 v[140:143], v149, s[0:1]
	v_add_u32_e32 v149, 0x2000, v149
	ds_read_b32 v133, v148 offset:256
	global_load_dwordx4 v[144:147], v149, s[0:1]
	v_add_u32_e32 v149, 0x2000, v149
	ds_read_b32 v134, v148 offset:512
	s_waitcnt vmcnt(2) lgkmcnt(2)
	v_mfma_f32_16x16x4_f32 v[88:91], v132, v136, v[88:91]
	v_mfma_f32_16x16x4_f32 v[92:95], v132, v137, v[92:95]
	v_mfma_f32_16x16x4_f32 v[112:115], v132, v138, v[112:115]
	v_mfma_f32_16x16x4_f32 v[116:119], v132, v139, v[116:119]
	global_load_dwordx4 v[136:139], v149, s[0:1]
	v_add_u32_e32 v149, 0x2000, v149
	ds_read_b32 v132, v148 offset:768
	s_waitcnt vmcnt(2) lgkmcnt(2)
	v_mfma_f32_16x16x4_f32 v[88:91], v133, v140, v[88:91]
	v_mfma_f32_16x16x4_f32 v[92:95], v133, v141, v[92:95]
	v_mfma_f32_16x16x4_f32 v[112:115], v133, v142, v[112:115]
	v_mfma_f32_16x16x4_f32 v[116:119], v133, v143, v[116:119]
	global_load_dwordx4 v[140:143], v149, s[0:1]
	v_add_u32_e32 v149, 0x2000, v149
	ds_read_b32 v133, v148 offset:1024
	s_waitcnt vmcnt(2) lgkmcnt(2)
	v_mfma_f32_16x16x4_f32 v[88:91], v134, v144, v[88:91]
	v_mfma_f32_16x16x4_f32 v[92:95], v134, v145, v[92:95]
	v_mfma_f32_16x16x4_f32 v[112:115], v134, v146, v[112:115]
	v_mfma_f32_16x16x4_f32 v[116:119], v134, v147, v[116:119]
	global_load_dwordx4 v[144:147], v149, s[0:1]
	v_add_u32_e32 v149, 0x2000, v149
	ds_read_b32 v134, v148 offset:1280
	s_waitcnt vmcnt(2) lgkmcnt(2)
	v_mfma_f32_16x16x4_f32 v[88:91], v132, v136, v[88:91]
	v_mfma_f32_16x16x4_f32 v[92:95], v132, v137, v[92:95]
	v_mfma_f32_16x16x4_f32 v[112:115], v132, v138, v[112:115]
	v_mfma_f32_16x16x4_f32 v[116:119], v132, v139, v[116:119]
	global_load_dwordx4 v[136:139], v149, s[0:1]
	v_add_u32_e32 v149, 0x2000, v149
	ds_read_b32 v132, v148 offset:1536
	s_waitcnt vmcnt(2) lgkmcnt(2)
	v_mfma_f32_16x16x4_f32 v[88:91], v133, v140, v[88:91]
	v_mfma_f32_16x16x4_f32 v[92:95], v133, v141, v[92:95]
	v_mfma_f32_16x16x4_f32 v[112:115], v133, v142, v[112:115]
	v_mfma_f32_16x16x4_f32 v[116:119], v133, v143, v[116:119]
	global_load_dwordx4 v[140:143], v149, s[0:1]
	v_add_u32_e32 v149, 0x2000, v149
	ds_read_b32 v133, v148 offset:1792
	s_waitcnt vmcnt(2) lgkmcnt(2)
	v_mfma_f32_16x16x4_f32 v[88:91], v134, v144, v[88:91]
	v_mfma_f32_16x16x4_f32 v[92:95], v134, v145, v[92:95]
	v_mfma_f32_16x16x4_f32 v[112:115], v134, v146, v[112:115]
	v_mfma_f32_16x16x4_f32 v[116:119], v134, v147, v[116:119]
	global_load_dwordx4 v[144:147], v149, s[0:1]
	v_add_u32_e32 v149, 0x2000, v149
	ds_read_b32 v134, v148 offset:2048
	s_waitcnt vmcnt(2) lgkmcnt(2)
	v_mfma_f32_16x16x4_f32 v[88:91], v132, v136, v[88:91]
	v_mfma_f32_16x16x4_f32 v[92:95], v132, v137, v[92:95]
	v_mfma_f32_16x16x4_f32 v[112:115], v132, v138, v[112:115]
	v_mfma_f32_16x16x4_f32 v[116:119], v132, v139, v[116:119]
	global_load_dwordx4 v[136:139], v149, s[0:1]
	v_add_u32_e32 v149, 0x2000, v149
	ds_read_b32 v132, v148 offset:2304
	s_waitcnt vmcnt(2) lgkmcnt(2)
	v_mfma_f32_16x16x4_f32 v[88:91], v133, v140, v[88:91]
	v_mfma_f32_16x16x4_f32 v[92:95], v133, v141, v[92:95]
	v_mfma_f32_16x16x4_f32 v[112:115], v133, v142, v[112:115]
	v_mfma_f32_16x16x4_f32 v[116:119], v133, v143, v[116:119]
	global_load_dwordx4 v[140:143], v149, s[0:1]
	v_add_u32_e32 v149, 0x2000, v149
	ds_read_b32 v133, v148 offset:2560
	s_waitcnt vmcnt(2) lgkmcnt(2)
	v_mfma_f32_16x16x4_f32 v[88:91], v134, v144, v[88:91]
	v_mfma_f32_16x16x4_f32 v[92:95], v134, v145, v[92:95]
	v_mfma_f32_16x16x4_f32 v[112:115], v134, v146, v[112:115]
	v_mfma_f32_16x16x4_f32 v[116:119], v134, v147, v[116:119]
	global_load_dwordx4 v[144:147], v149, s[0:1]
	v_add_u32_e32 v149, 0x2000, v149
	ds_read_b32 v134, v148 offset:2816
	s_waitcnt vmcnt(2) lgkmcnt(2)
	v_mfma_f32_16x16x4_f32 v[88:91], v132, v136, v[88:91]
	v_mfma_f32_16x16x4_f32 v[92:95], v132, v137, v[92:95]
	v_mfma_f32_16x16x4_f32 v[112:115], v132, v138, v[112:115]
	v_mfma_f32_16x16x4_f32 v[116:119], v132, v139, v[116:119]
	global_load_dwordx4 v[136:139], v149, s[0:1]
	v_add_u32_e32 v149, 0x2000, v149
	ds_read_b32 v132, v148 offset:3072
	s_waitcnt vmcnt(2) lgkmcnt(2)
	v_mfma_f32_16x16x4_f32 v[88:91], v133, v140, v[88:91]
	v_mfma_f32_16x16x4_f32 v[92:95], v133, v141, v[92:95]
	v_mfma_f32_16x16x4_f32 v[112:115], v133, v142, v[112:115]
	v_mfma_f32_16x16x4_f32 v[116:119], v133, v143, v[116:119]
	global_load_dwordx4 v[140:143], v149, s[0:1]
	v_add_u32_e32 v149, 0x2000, v149
	ds_read_b32 v133, v148 offset:3328
	s_waitcnt vmcnt(2) lgkmcnt(2)
	v_mfma_f32_16x16x4_f32 v[88:91], v134, v144, v[88:91]
	v_mfma_f32_16x16x4_f32 v[92:95], v134, v145, v[92:95]
	v_mfma_f32_16x16x4_f32 v[112:115], v134, v146, v[112:115]
	v_mfma_f32_16x16x4_f32 v[116:119], v134, v147, v[116:119]
	global_load_dwordx4 v[144:147], v149, s[0:1]
	v_add_u32_e32 v149, 0x2000, v149
	ds_read_b32 v134, v148 offset:3584
	s_waitcnt vmcnt(2) lgkmcnt(2)
	v_mfma_f32_16x16x4_f32 v[88:91], v132, v136, v[88:91]
	v_mfma_f32_16x16x4_f32 v[92:95], v132, v137, v[92:95]
	v_mfma_f32_16x16x4_f32 v[112:115], v132, v138, v[112:115]
	v_mfma_f32_16x16x4_f32 v[116:119], v132, v139, v[116:119]
	global_load_dwordx4 v[136:139], v149, s[0:1]
	v_add_u32_e32 v149, 0x2000, v149
	ds_read_b32 v132, v148 offset:3840
	s_waitcnt vmcnt(2) lgkmcnt(2)
	v_mfma_f32_16x16x4_f32 v[88:91], v133, v140, v[88:91]
	v_mfma_f32_16x16x4_f32 v[92:95], v133, v141, v[92:95]
	v_mfma_f32_16x16x4_f32 v[112:115], v133, v142, v[112:115]
	v_mfma_f32_16x16x4_f32 v[116:119], v133, v143, v[116:119]
	global_load_dwordx4 v[140:143], v149, s[0:1]
	v_add_u32_e32 v149, 0x2000, v149
	ds_read_b32 v133, v148 offset:4096
	s_waitcnt vmcnt(2) lgkmcnt(2)
	v_mfma_f32_16x16x4_f32 v[88:91], v134, v144, v[88:91]
	v_mfma_f32_16x16x4_f32 v[92:95], v134, v145, v[92:95]
	v_mfma_f32_16x16x4_f32 v[112:115], v134, v146, v[112:115]
	v_mfma_f32_16x16x4_f32 v[116:119], v134, v147, v[116:119]
	global_load_dwordx4 v[144:147], v149, s[0:1]
	v_add_u32_e32 v149, 0x2000, v149
	ds_read_b32 v134, v148 offset:4352
	s_waitcnt vmcnt(2) lgkmcnt(2)
	v_mfma_f32_16x16x4_f32 v[88:91], v132, v136, v[88:91]
	v_mfma_f32_16x16x4_f32 v[92:95], v132, v137, v[92:95]
	v_mfma_f32_16x16x4_f32 v[112:115], v132, v138, v[112:115]
	v_mfma_f32_16x16x4_f32 v[116:119], v132, v139, v[116:119]
	global_load_dwordx4 v[136:139], v149, s[0:1]
	v_add_u32_e32 v149, 0x2000, v149
	ds_read_b32 v132, v148 offset:4608
	s_waitcnt vmcnt(2) lgkmcnt(2)
	v_mfma_f32_16x16x4_f32 v[88:91], v133, v140, v[88:91]
	v_mfma_f32_16x16x4_f32 v[92:95], v133, v141, v[92:95]
	v_mfma_f32_16x16x4_f32 v[112:115], v133, v142, v[112:115]
	v_mfma_f32_16x16x4_f32 v[116:119], v133, v143, v[116:119]
	global_load_dwordx4 v[140:143], v149, s[0:1]
	v_add_u32_e32 v149, 0x2000, v149
	ds_read_b32 v133, v148 offset:4864
	s_waitcnt vmcnt(2) lgkmcnt(2)
	v_mfma_f32_16x16x4_f32 v[88:91], v134, v144, v[88:91]
	v_mfma_f32_16x16x4_f32 v[92:95], v134, v145, v[92:95]
	v_mfma_f32_16x16x4_f32 v[112:115], v134, v146, v[112:115]
	v_mfma_f32_16x16x4_f32 v[116:119], v134, v147, v[116:119]
	global_load_dwordx4 v[144:147], v149, s[0:1]
	v_add_u32_e32 v149, 0x2000, v149
	ds_read_b32 v134, v148 offset:5120
	s_waitcnt vmcnt(2) lgkmcnt(2)
	v_mfma_f32_16x16x4_f32 v[88:91], v132, v136, v[88:91]
	v_mfma_f32_16x16x4_f32 v[92:95], v132, v137, v[92:95]
	v_mfma_f32_16x16x4_f32 v[112:115], v132, v138, v[112:115]
	v_mfma_f32_16x16x4_f32 v[116:119], v132, v139, v[116:119]
	global_load_dwordx4 v[136:139], v149, s[0:1]
	v_add_u32_e32 v149, 0x2000, v149
	ds_read_b32 v132, v148 offset:5376
	s_waitcnt vmcnt(2) lgkmcnt(2)
	v_mfma_f32_16x16x4_f32 v[88:91], v133, v140, v[88:91]
	v_mfma_f32_16x16x4_f32 v[92:95], v133, v141, v[92:95]
	v_mfma_f32_16x16x4_f32 v[112:115], v133, v142, v[112:115]
	v_mfma_f32_16x16x4_f32 v[116:119], v133, v143, v[116:119]
	global_load_dwordx4 v[140:143], v149, s[0:1]
	v_add_u32_e32 v149, 0x2000, v149
	ds_read_b32 v133, v148 offset:5632
	s_waitcnt vmcnt(2) lgkmcnt(2)
	v_mfma_f32_16x16x4_f32 v[88:91], v134, v144, v[88:91]
	v_mfma_f32_16x16x4_f32 v[92:95], v134, v145, v[92:95]
	v_mfma_f32_16x16x4_f32 v[112:115], v134, v146, v[112:115]
	v_mfma_f32_16x16x4_f32 v[116:119], v134, v147, v[116:119]
	global_load_dwordx4 v[144:147], v149, s[0:1]
	v_add_u32_e32 v149, 0x2000, v149
	ds_read_b32 v134, v148 offset:5888
	s_waitcnt vmcnt(2) lgkmcnt(2)
	v_mfma_f32_16x16x4_f32 v[88:91], v132, v136, v[88:91]
	v_mfma_f32_16x16x4_f32 v[92:95], v132, v137, v[92:95]
	v_mfma_f32_16x16x4_f32 v[112:115], v132, v138, v[112:115]
	v_mfma_f32_16x16x4_f32 v[116:119], v132, v139, v[116:119]
	global_load_dwordx4 v[136:139], v149, s[0:1]
	v_add_u32_e32 v149, 0x2000, v149
	ds_read_b32 v132, v148 offset:6144
	s_waitcnt vmcnt(2) lgkmcnt(2)
	v_mfma_f32_16x16x4_f32 v[88:91], v133, v140, v[88:91]
	v_mfma_f32_16x16x4_f32 v[92:95], v133, v141, v[92:95]
	v_mfma_f32_16x16x4_f32 v[112:115], v133, v142, v[112:115]
	v_mfma_f32_16x16x4_f32 v[116:119], v133, v143, v[116:119]
	global_load_dwordx4 v[140:143], v149, s[0:1]
	v_add_u32_e32 v149, 0x2000, v149
	ds_read_b32 v133, v148 offset:6400
	s_waitcnt vmcnt(2) lgkmcnt(2)
	v_mfma_f32_16x16x4_f32 v[88:91], v134, v144, v[88:91]
	v_mfma_f32_16x16x4_f32 v[92:95], v134, v145, v[92:95]
	v_mfma_f32_16x16x4_f32 v[112:115], v134, v146, v[112:115]
	v_mfma_f32_16x16x4_f32 v[116:119], v134, v147, v[116:119]
	global_load_dwordx4 v[144:147], v149, s[0:1]
	v_add_u32_e32 v149, 0x2000, v149
	ds_read_b32 v134, v148 offset:6656
	s_waitcnt vmcnt(2) lgkmcnt(2)
	v_mfma_f32_16x16x4_f32 v[88:91], v132, v136, v[88:91]
	v_mfma_f32_16x16x4_f32 v[92:95], v132, v137, v[92:95]
	v_mfma_f32_16x16x4_f32 v[112:115], v132, v138, v[112:115]
	v_mfma_f32_16x16x4_f32 v[116:119], v132, v139, v[116:119]
	global_load_dwordx4 v[136:139], v149, s[0:1]
	v_add_u32_e32 v149, 0x2000, v149
	ds_read_b32 v132, v148 offset:6912
	s_waitcnt vmcnt(2) lgkmcnt(2)
	v_mfma_f32_16x16x4_f32 v[88:91], v133, v140, v[88:91]
	v_mfma_f32_16x16x4_f32 v[92:95], v133, v141, v[92:95]
	v_mfma_f32_16x16x4_f32 v[112:115], v133, v142, v[112:115]
	v_mfma_f32_16x16x4_f32 v[116:119], v133, v143, v[116:119]
	global_load_dwordx4 v[140:143], v149, s[0:1]
	v_add_u32_e32 v149, 0x2000, v149
	ds_read_b32 v133, v148 offset:7168
	s_waitcnt vmcnt(2) lgkmcnt(2)
	v_mfma_f32_16x16x4_f32 v[88:91], v134, v144, v[88:91]
	v_mfma_f32_16x16x4_f32 v[92:95], v134, v145, v[92:95]
	v_mfma_f32_16x16x4_f32 v[112:115], v134, v146, v[112:115]
	v_mfma_f32_16x16x4_f32 v[116:119], v134, v147, v[116:119]
	global_load_dwordx4 v[144:147], v149, s[0:1]
	v_add_u32_e32 v149, 0x2000, v149
	ds_read_b32 v134, v148 offset:7424
	s_waitcnt vmcnt(2) lgkmcnt(2)
	v_mfma_f32_16x16x4_f32 v[88:91], v132, v136, v[88:91]
	v_mfma_f32_16x16x4_f32 v[92:95], v132, v137, v[92:95]
	v_mfma_f32_16x16x4_f32 v[112:115], v132, v138, v[112:115]
	v_mfma_f32_16x16x4_f32 v[116:119], v132, v139, v[116:119]
	global_load_dwordx4 v[136:139], v149, s[0:1]
	v_add_u32_e32 v149, 0x2000, v149
	ds_read_b32 v132, v148 offset:7680
	s_waitcnt vmcnt(2) lgkmcnt(2)
	v_mfma_f32_16x16x4_f32 v[88:91], v133, v140, v[88:91]
	v_mfma_f32_16x16x4_f32 v[92:95], v133, v141, v[92:95]
	v_mfma_f32_16x16x4_f32 v[112:115], v133, v142, v[112:115]
	v_mfma_f32_16x16x4_f32 v[116:119], v133, v143, v[116:119]
	global_load_dwordx4 v[140:143], v149, s[0:1]
	v_add_u32_e32 v149, 0x2000, v149
	ds_read_b32 v133, v148 offset:7936
	s_waitcnt vmcnt(2) lgkmcnt(2)
	v_mfma_f32_16x16x4_f32 v[88:91], v134, v144, v[88:91]
	v_mfma_f32_16x16x4_f32 v[92:95], v134, v145, v[92:95]
	v_mfma_f32_16x16x4_f32 v[112:115], v134, v146, v[112:115]
	v_mfma_f32_16x16x4_f32 v[116:119], v134, v147, v[116:119]
	s_waitcnt vmcnt(1) lgkmcnt(1)
	v_mfma_f32_16x16x4_f32 v[88:91], v132, v136, v[88:91]
	v_mfma_f32_16x16x4_f32 v[92:95], v132, v137, v[92:95]
	v_mfma_f32_16x16x4_f32 v[112:115], v132, v138, v[112:115]
	v_mfma_f32_16x16x4_f32 v[116:119], v132, v139, v[116:119]
	s_waitcnt vmcnt(0) lgkmcnt(0)
	v_mfma_f32_16x16x4_f32 v[88:91], v133, v140, v[88:91]
	v_mfma_f32_16x16x4_f32 v[92:95], v133, v141, v[92:95]
	v_mfma_f32_16x16x4_f32 v[112:115], v133, v142, v[112:115]
	v_mfma_f32_16x16x4_f32 v[116:119], v133, v143, v[116:119]
	s_nop 15
	s_nop 3
	s_mov_b32 s46, 0
	s_mov_b64 s[24:25], -1
	ds_write_b32 v150, v88 offset:0
	ds_write_b32 v150, v89 offset:2048
	ds_write_b32 v150, v90 offset:4096
	ds_write_b32 v150, v91 offset:6144
	ds_write_b32 v150, v92 offset:4
	ds_write_b32 v150, v93 offset:2052
	ds_write_b32 v150, v94 offset:4100
	ds_write_b32 v150, v95 offset:6148
	ds_write_b32 v150, v112 offset:8
	ds_write_b32 v150, v113 offset:2056
	ds_write_b32 v150, v114 offset:4104
	ds_write_b32 v150, v115 offset:6152
	ds_write_b32 v150, v116 offset:12
	ds_write_b32 v150, v117 offset:2060
	ds_write_b32 v150, v118 offset:4108
	ds_write_b32 v150, v119 offset:6156
	s_waitcnt lgkmcnt(0)
	s_barrier
